# adds write-through (sc1) on the P1 H row stores (full 1 KiB lines per instruction) on top of the nt streaming loads
# speedup vs baseline: 1.0429x; 1.0067x over previous
; __device__ __forceinline__ int fresh_tid() { int t = threadIdx.x; asm volatile("" : "+v"(t)); return t; }
; __device__ __forceinline__ void p1_prompt_rows(const Params& p) {
;     const int tid = fresh_tid(), lane = tid & 63, gw = blockIdx.x * 8 + (tid >> 6);
;     const float* mb = (const float*)(p.ws + WS_MOD) + (size_t)(gw >> 8) * NMOD; bf16_t* H = (bf16_t*)(p.ws + WS_H);
;     f32x4 gs[4], sh[4];
; #pragma unroll
;     for (int i = 0; i < 4; ++i) { const int c = (i >> 1) * 512 + lane * 8 + (i & 1) * 4; gs[i] = *(const f32x4*)(p.g_mix + c) * (*(const f32x4*)(mb + 1024 + c) + 1.f); sh[i] = *(const f32x4*)(mb + c); }
; #pragma unroll
;     for (int trip = 0; trip < 2; ++trip) { const int rowb = gw * 8 + trip * 4;
;         f32x4 v[4][4];
; #pragma unroll
;         for (int q = 0; q < 4; ++q)
; #pragma unroll
;             for (int i = 0; i < 4; ++i) v[q][i] = *(const f32x4*)(p.x_prompt + (size_t)(rowb + q) * DM + (i >> 1) * 512 + lane * 8 + (i & 1) * 4);
;         __builtin_amdgcn_sched_barrier(0);
; #pragma unroll
;         for (int q = 0; q < 4; ++q) { float ss = 0.f;
; #pragma unroll
;             for (int i = 0; i < 4; ++i) ss += v[q][i][0] * v[q][i][0] + v[q][i][1] * v[q][i][1] + v[q][i][2] * v[q][i][2] + v[q][i][3] * v[q][i][3];
; #pragma unroll
;             for (int o = 1; o < 64; o <<= 1) ss += __shfl_xor(ss, o);
.LBB0_133:
	s_or_b64 exec, exec, s[0:1]
	s_add_u32 s26, s58, 0x1a70000
	v_mov_b32_e32 v2, v224
	s_addc_u32 s27, s59, 0
	s_waitcnt lgkmcnt(0)
	s_barrier
	s_lshl_b32 s95, s2, 3
	s_mov_b64 s[10:11], 0x1000
	v_ashrrev_i32_e32 v0, 6, v2
	v_add_u32_e32 v20, s95, v0
	v_lshrrev_b32_e32 v0, 8, v20
	v_lshlrev_b32_e32 v2, 3, v2
	v_mul_hi_i32_i24_e32 v1, 0x6000, v0
	v_mul_i32_i24_e32 v0, 0x6000, v0
	v_and_b32_e32 v126, 0x1f8, v2
	v_lshl_add_u64 v[0:1], s[16:17], 0, v[0:1]
	v_lshlrev_b32_e32 v80, 2, v126
	v_mov_b32_e32 v81, 0
	v_lshl_add_u64 v[4:5], v[0:1], 0, s[10:11]
	v_or_b32_e32 v6, 0x800, v80
	v_mov_b32_e32 v7, v81
	v_lshlrev_b32_e32 v102, 3, v20
	v_lshl_add_u64 v[2:3], v[4:5], 0, v[80:81]
	v_lshl_add_u64 v[16:17], v[0:1], 0, v[80:81]
	v_lshl_add_u64 v[18:19], v[4:5], 0, v[6:7]
	v_ashrrev_i32_e32 v103, 31, v102
	global_load_dwordx4 v[82:85], v80, s[46:47] offset:16
	global_load_dwordx4 v[86:89], v80, s[46:47]
	global_load_dwordx4 v[90:93], v[2:3], off offset:16
	global_load_dwordx4 v[94:97], v[2:3], off
	s_nop 0
	global_load_dwordx4 v[0:3], v[16:17], off offset:16
	global_load_dwordx4 v[8:11], v[16:17], off
	global_load_dwordx4 v[112:115], v80, s[46:47] offset:2064
	global_load_dwordx4 v[116:119], v80, s[46:47] offset:2048
	global_load_dwordx4 v[98:101], v[18:19], off offset:16
	global_load_dwordx4 v[120:123], v[18:19], off
	global_load_dwordx4 v[4:7], v[16:17], off offset:2064
	global_load_dwordx4 v[12:15], v[16:17], off offset:2048
	v_lshl_add_u64 v[104:105], s[36:37], 0, v[80:81]
	v_lshlrev_b64 v[16:17], 12, v[102:103]
	v_or_b32_e32 v110, 1, v102
	v_lshl_add_u64 v[16:17], v[104:105], 0, v[16:17]
	v_ashrrev_i32_e32 v111, 31, v110
	global_load_dwordx4 v[76:79], v[16:17], off nt
	global_load_dwordx4 v[72:75], v[16:17], off offset:16 nt
	global_load_dwordx4 v[68:71], v[16:17], off offset:2048 nt
	global_load_dwordx4 v[64:67], v[16:17], off offset:2064 nt
	v_lshlrev_b64 v[16:17], 12, v[110:111]
	v_or_b32_e32 v108, 2, v102
	v_lshl_add_u64 v[16:17], v[104:105], 0, v[16:17]
	v_ashrrev_i32_e32 v109, 31, v108
	global_load_dwordx4 v[60:63], v[16:17], off nt
	global_load_dwordx4 v[56:59], v[16:17], off offset:16 nt
	global_load_dwordx4 v[52:55], v[16:17], off offset:2048 nt
	global_load_dwordx4 v[48:51], v[16:17], off offset:2064 nt
	v_lshlrev_b64 v[16:17], 12, v[108:109]
	v_or_b32_e32 v106, 3, v102
	v_lshl_add_u64 v[16:17], v[104:105], 0, v[16:17]
	v_ashrrev_i32_e32 v107, 31, v106
	global_load_dwordx4 v[44:47], v[16:17], off nt
	global_load_dwordx4 v[40:43], v[16:17], off offset:16 nt
	global_load_dwordx4 v[36:39], v[16:17], off offset:2048 nt
	global_load_dwordx4 v[32:35], v[16:17], off offset:2064 nt
	v_lshlrev_b64 v[16:17], 12, v[106:107]
	v_lshl_add_u64 v[124:125], v[104:105], 0, v[16:17]
	global_load_dwordx4 v[28:31], v[124:125], off nt
	global_load_dwordx4 v[24:27], v[124:125], off offset:16 nt
	global_load_dwordx4 v[20:23], v[124:125], off offset:2048 nt
	global_load_dwordx4 v[16:19], v[124:125], off offset:2064 nt
	v_mbcnt_lo_u32_b32 v80, -1, 0
	v_mbcnt_hi_u32_b32 v80, -1, v80
	s_movk_i32 s12, 0x4000
	s_movk_i32 s13, 0x6000
	s_lshl_b32 s94, s34, 3
	s_add_i32 s97, s95, 0x4000
	s_waitcnt vmcnt(19)
	v_pk_add_f32 v[124:125], v[98:99], 1.0 op_sel_hi:[1,0]
	v_pk_add_f32 v[94:95], v[94:95], 1.0 op_sel_hi:[1,0]
	v_pk_add_f32 v[90:91], v[90:91], 1.0 op_sel_hi:[1,0]
	s_waitcnt vmcnt(18)
	v_pk_add_f32 v[120:121], v[120:121], 1.0 op_sel_hi:[1,0]
	v_pk_mul_f32 v[98:99], v[86:87], v[94:95]
	v_pk_mul_f32 v[94:95], v[82:83], v[90:91]
	v_and_b32_e32 v82, 64, v80
	v_pk_add_f32 v[96:97], v[96:97], 1.0 op_sel_hi:[1,0]
	v_pk_add_f32 v[92:93], v[92:93], 1.0 op_sel_hi:[1,0]
	v_pk_add_f32 v[122:123], v[122:123], 1.0 op_sel_hi:[1,0]
	v_pk_add_f32 v[100:101], v[100:101], 1.0 op_sel_hi:[1,0]
	v_pk_mul_f32 v[90:91], v[116:117], v[120:121]
	v_add_u32_e32 v116, 64, v82
	v_lshlrev_b32_e32 v82, 1, v126
	v_mov_b32_e32 v83, v81
	v_pk_mul_f32 v[96:97], v[88:89], v[96:97]
	v_pk_mul_f32 v[92:93], v[84:85], v[92:93]
	v_pk_mul_f32 v[88:89], v[118:119], v[122:123]
	v_pk_mul_f32 v[84:85], v[114:115], v[100:101]
	v_pk_mul_f32 v[86:87], v[112:113], v[124:125]
	v_lshl_add_u64 v[100:101], s[26:27], 0, v[82:83]
	s_waitcnt vmcnt(15)
	v_mov_b32_e32 v112, v77
	s_waitcnt vmcnt(14)
	v_mov_b32_e32 v113, v73
	v_mov_b32_e32 v82, v76
	v_mov_b32_e32 v83, v72
	v_pk_mul_f32 v[112:113], v[112:113], v[112:113]
	s_waitcnt vmcnt(13)
	v_mov_b32_e32 v114, v69
	v_pk_fma_f32 v[82:83], v[82:83], v[82:83], v[112:113]
	v_mov_b32_e32 v112, v78
	v_mov_b32_e32 v113, v74
	v_pk_fma_f32 v[82:83], v[112:113], v[112:113], v[82:83]
	v_mov_b32_e32 v112, v79
	v_mov_b32_e32 v113, v75
	s_waitcnt vmcnt(12)
	v_mov_b32_e32 v115, v65
	v_pk_fma_f32 v[82:83], v[112:113], v[112:113], v[82:83]
	v_mov_b32_e32 v112, v68
	v_mov_b32_e32 v113, v64
	v_pk_mul_f32 v[114:115], v[114:115], v[114:115]
	v_add_f32_e32 v82, v82, v83
	v_pk_fma_f32 v[112:113], v[112:113], v[112:113], v[114:115]
	v_mov_b32_e32 v114, v70
	v_mov_b32_e32 v115, v66
	v_pk_fma_f32 v[112:113], v[114:115], v[114:115], v[112:113]
	v_mov_b32_e32 v114, v71
	v_mov_b32_e32 v115, v67
	v_xor_b32_e32 v83, 1, v80
	v_pk_fma_f32 v[112:113], v[114:115], v[114:115], v[112:113]
	v_cmp_lt_i32_e32 vcc, v83, v116
	v_add_f32_e32 v82, v82, v112
	v_add_f32_e32 v82, v82, v113
	v_cndmask_b32_e32 v83, v80, v83, vcc
	v_lshlrev_b32_e32 v225, 2, v83
	ds_bpermute_b32 v83, v225, v82
	s_mov_b32 s15, 0x800000
	s_waitcnt vmcnt(10)
	v_mov_b32_e32 v117, v57
	v_mov_b32_e32 v114, v60
	v_mov_b32_e32 v115, v56
	s_waitcnt lgkmcnt(0)
	v_add_f32_e32 v82, v82, v83
	v_xor_b32_e32 v83, 2, v80
	v_cmp_lt_i32_e32 vcc, v83, v116
	s_waitcnt vmcnt(9)
	v_mov_b32_e32 v118, v53
	s_waitcnt vmcnt(8)
; __device__ __forceinline__ void st_bf16x8(bf16_t* p, const f32x4 a, const f32x4 b) { uint4 o; o.x = cvt_pk_bf16(a[0], a[1]); o.y = cvt_pk_bf16(a[2], a[3]); o.z = cvt_pk_bf16(b[0], b[1]); o.w = cvt_pk_bf16(b[2], b[3]); *(uint4*)p = o; }
; __device__ __forceinline__ void p1_prompt_rows(const Params& p) {
;     ...
;         for (int q = 0; q < 4; ++q) { float ss = 0.f;
; #pragma unroll
;             for (int i = 0; i < 4; ++i) ss += v[q][i][0] * v[q][i][0] + v[q][i][1] * v[q][i][1] + v[q][i][2] * v[q][i][2] + v[q][i][3] * v[q][i][3];
; #pragma unroll
;             for (int o = 1; o < 64; o <<= 1) ss += __shfl_xor(ss, o);
;             const float rs = rsqrtf(ss * (1.f / DM) + EPS);
; #pragma unroll
;             for (int h = 0; h < 2; ++h) st_bf16x8(H + (size_t)(rowb + q) * DM + h * 512 + lane * 8, v[q][2 * h] * rs * gs[2 * h] + sh[2 * h], v[q][2 * h + 1] * rs * gs[2 * h + 1] + sh[2 * h + 1]); }
	v_mov_b32_e32 v119, v49
	v_cndmask_b32_e32 v83, v80, v83, vcc
	v_lshlrev_b32_e32 v226, 2, v83
	ds_bpermute_b32 v83, v226, v82
	v_pk_mul_f32 v[118:119], v[118:119], v[118:119]
	v_lshlrev_b64 v[112:113], 11, v[102:103]
	v_lshl_add_u64 v[112:113], v[100:101], 0, v[112:113]
	s_mov_b32 s14, 0x3a800000
	s_waitcnt lgkmcnt(0)
	v_add_f32_e32 v82, v82, v83
	v_xor_b32_e32 v83, 4, v80
	v_cmp_lt_i32_e32 vcc, v83, v116
	s_nop 1
	v_cndmask_b32_e32 v83, v80, v83, vcc
	v_lshlrev_b32_e32 v227, 2, v83
	ds_bpermute_b32 v83, v227, v82
	s_waitcnt lgkmcnt(0)
	v_add_f32_e32 v82, v82, v83
	v_xor_b32_e32 v83, 8, v80
	v_cmp_lt_i32_e32 vcc, v83, v116
	s_nop 1
	v_cndmask_b32_e32 v83, v80, v83, vcc
	v_lshlrev_b32_e32 v228, 2, v83
	ds_bpermute_b32 v83, v228, v82
	s_waitcnt lgkmcnt(0)
	v_add_f32_e32 v82, v82, v83
	v_xor_b32_e32 v83, 16, v80
	v_cmp_lt_i32_e32 vcc, v83, v116
	s_nop 1
	v_cndmask_b32_e32 v83, v80, v83, vcc
	v_lshlrev_b32_e32 v229, 2, v83
	ds_bpermute_b32 v83, v229, v82
	s_waitcnt lgkmcnt(0)
	v_add_f32_e32 v82, v82, v83
	v_xor_b32_e32 v83, 32, v80
	v_cmp_lt_i32_e32 vcc, v83, v116
	v_mov_b32_e32 v116, v61
	v_pk_mul_f32 v[116:117], v[116:117], v[116:117]
	v_cndmask_b32_e32 v80, v80, v83, vcc
	v_lshlrev_b32_e32 v230, 2, v80
	ds_bpermute_b32 v80, v230, v82
	v_pk_fma_f32 v[114:115], v[114:115], v[114:115], v[116:117]
	v_mov_b32_e32 v116, v62
	v_mov_b32_e32 v117, v58
	v_pk_fma_f32 v[114:115], v[116:117], v[116:117], v[114:115]
	s_waitcnt lgkmcnt(0)
	v_add_f32_e32 v80, v82, v80
	v_mov_b32_e32 v82, 0x358637bd
	v_fmamk_f32 v80, v80, 0x3a800000, v82
	v_mul_f32_e32 v83, 0x4b800000, v80
	v_cmp_gt_f32_e32 vcc, s15, v80
	v_mov_b32_e32 v116, v63
	v_mov_b32_e32 v117, v59
	v_cndmask_b32_e32 v80, v80, v83, vcc
	v_rsq_f32_e32 v80, v80
	v_pk_fma_f32 v[114:115], v[116:117], v[116:117], v[114:115]
	v_mov_b32_e32 v116, v52
	v_mov_b32_e32 v117, v48
	v_pk_fma_f32 v[116:117], v[116:117], v[116:117], v[118:119]
	v_mov_b32_e32 v118, v54
	v_mov_b32_e32 v119, v50
	v_mul_f32_e32 v83, 0x45800000, v80
	v_pk_fma_f32 v[116:117], v[118:119], v[118:119], v[116:117]
	v_mov_b32_e32 v118, v55
	v_mov_b32_e32 v119, v51
	v_cndmask_b32_e32 v80, v80, v83, vcc
	v_pk_fma_f32 v[116:117], v[118:119], v[118:119], v[116:117]
	v_add_f32_e32 v83, v114, v115
	v_add_f32_e32 v83, v83, v116
	v_add_f32_e32 v83, v83, v117
	ds_bpermute_b32 v103, v225, v83
	v_pk_mul_f32 v[76:77], v[76:77], v[80:81] op_sel_hi:[1,0]
	v_pk_mul_f32 v[72:73], v[72:73], v[80:81] op_sel_hi:[1,0]
	v_pk_fma_f32 v[76:77], v[98:99], v[76:77], v[8:9]
	v_pk_mul_f32 v[74:75], v[74:75], v[80:81] op_sel_hi:[1,0]
	s_waitcnt lgkmcnt(0)
	v_add_f32_e32 v83, v83, v103
	ds_bpermute_b32 v103, v226, v83
	v_pk_fma_f32 v[114:115], v[92:93], v[74:75], v[2:3]
	v_pk_fma_f32 v[74:75], v[94:95], v[72:73], v[0:1]
	v_cvt_pk_bf16_f32 v72, v76, v77
	v_pk_mul_f32 v[78:79], v[78:79], v[80:81] op_sel_hi:[1,0]
	s_waitcnt lgkmcnt(0)
	v_add_f32_e32 v83, v83, v103
	ds_bpermute_b32 v103, v227, v83
	v_pk_fma_f32 v[78:79], v[96:97], v[78:79], v[10:11]
	v_cvt_pk_bf16_f32 v74, v74, v75
	v_cvt_pk_bf16_f32 v75, v114, v115
	v_pk_mul_f32 v[68:69], v[68:69], v[80:81] op_sel_hi:[1,0]
	s_waitcnt lgkmcnt(0)
	v_add_f32_e32 v76, v83, v103
	ds_bpermute_b32 v77, v228, v76
	v_cvt_pk_bf16_f32 v73, v78, v79
	global_store_dwordx4 v[112:113], v[72:75], off sc1
	v_pk_fma_f32 v[68:69], v[90:91], v[68:69], v[12:13]
	v_pk_mul_f32 v[64:65], v[64:65], v[80:81] op_sel_hi:[1,0]
	s_waitcnt lgkmcnt(0)
	v_add_f32_e32 v72, v76, v77
	ds_bpermute_b32 v73, v229, v72
	v_pk_mul_f32 v[66:67], v[66:67], v[80:81] op_sel_hi:[1,0]
	v_pk_mul_f32 v[70:71], v[70:71], v[80:81] op_sel_hi:[1,0]
	s_waitcnt lgkmcnt(0)
	v_add_f32_e32 v74, v72, v73
	ds_bpermute_b32 v75, v230, v74
	v_pk_fma_f32 v[72:73], v[84:85], v[66:67], v[6:7]
	v_pk_fma_f32 v[66:67], v[86:87], v[64:65], v[4:5]
	v_cvt_pk_bf16_f32 v64, v68, v69
	v_pk_fma_f32 v[70:71], v[88:89], v[70:71], v[14:15]
	s_waitcnt lgkmcnt(0)
	v_add_f32_e32 v68, v74, v75
	v_fmamk_f32 v68, v68, 0x3a800000, v82
	v_mul_f32_e32 v69, 0x4b800000, v68
	v_cmp_gt_f32_e32 vcc, s15, v68
	v_cvt_pk_bf16_f32 v65, v70, v71
	v_cvt_pk_bf16_f32 v66, v66, v67
	v_cvt_pk_bf16_f32 v67, v72, v73
	global_store_dwordx4 v[112:113], v[64:67], off offset:1024 sc1
	s_waitcnt vmcnt(9)
	v_mov_b32_e32 v70, v45
	v_cndmask_b32_e32 v68, v68, v69, vcc
	v_rsq_f32_e32 v68, v68
	s_waitcnt vmcnt(8)
	v_mov_b32_e32 v71, v41
	v_mov_b32_e32 v69, v40
	v_pk_mul_f32 v[70:71], v[70:71], v[70:71]
	v_mul_f32_e32 v64, 0x45800000, v68
	v_cndmask_b32_e32 v64, v68, v64, vcc
	v_mov_b32_e32 v68, v44
	v_pk_fma_f32 v[68:69], v[68:69], v[68:69], v[70:71]
	v_mov_b32_e32 v70, v46
	v_mov_b32_e32 v71, v42
	v_pk_fma_f32 v[68:69], v[70:71], v[70:71], v[68:69]
	v_mov_b32_e32 v70, v47
	v_mov_b32_e32 v71, v43
	s_waitcnt vmcnt(7)
	v_mov_b32_e32 v72, v37
	s_waitcnt vmcnt(6)
	v_mov_b32_e32 v73, v33
	v_pk_fma_f32 v[68:69], v[70:71], v[70:71], v[68:69]
	v_mov_b32_e32 v70, v36
	v_mov_b32_e32 v71, v32
	v_pk_mul_f32 v[72:73], v[72:73], v[72:73]
	v_add_f32_e32 v65, v68, v69
	v_pk_fma_f32 v[70:71], v[70:71], v[70:71], v[72:73]
	v_mov_b32_e32 v72, v38
	v_mov_b32_e32 v73, v34
	v_pk_fma_f32 v[70:71], v[72:73], v[72:73], v[70:71]
	v_mov_b32_e32 v72, v39
	v_mov_b32_e32 v73, v35
	v_pk_fma_f32 v[70:71], v[72:73], v[72:73], v[70:71]
	v_lshlrev_b64 v[66:67], 11, v[110:111]
	v_add_f32_e32 v65, v65, v70
	v_add_f32_e32 v65, v65, v71
	ds_bpermute_b32 v68, v225, v65
	v_pk_mul_f32 v[60:61], v[60:61], v[64:65] op_sel_hi:[1,0]
	v_pk_mul_f32 v[62:63], v[62:63], v[64:65] op_sel_hi:[1,0]
	v_pk_fma_f32 v[60:61], v[98:99], v[60:61], v[8:9]
	v_lshl_add_u64 v[66:67], v[100:101], 0, v[66:67]
	s_waitcnt lgkmcnt(0)
; __device__ __forceinline__ void st_bf16x8(bf16_t* p, const f32x4 a, const f32x4 b) { uint4 o; o.x = cvt_pk_bf16(a[0], a[1]); o.y = cvt_pk_bf16(a[2], a[3]); o.z = cvt_pk_bf16(b[0], b[1]); o.w = cvt_pk_bf16(b[2], b[3]); *(uint4*)p = o; }
; __device__ __forceinline__ void p1_prompt_rows(const Params& p) {
;     ...
;         for (int q = 0; q < 4; ++q) { float ss = 0.f;
; #pragma unroll
;             for (int i = 0; i < 4; ++i) ss += v[q][i][0] * v[q][i][0] + v[q][i][1] * v[q][i][1] + v[q][i][2] * v[q][i][2] + v[q][i][3] * v[q][i][3];
; #pragma unroll
;             for (int o = 1; o < 64; o <<= 1) ss += __shfl_xor(ss, o);
;             const float rs = rsqrtf(ss * (1.f / DM) + EPS);
; #pragma unroll
;             for (int h = 0; h < 2; ++h) st_bf16x8(H + (size_t)(rowb + q) * DM + h * 512 + lane * 8, v[q][2 * h] * rs * gs[2 * h] + sh[2 * h], v[q][2 * h + 1] * rs * gs[2 * h + 1] + sh[2 * h + 1]); }
	v_add_f32_e32 v65, v65, v68
	ds_bpermute_b32 v70, v226, v65
	v_pk_mul_f32 v[56:57], v[56:57], v[64:65] op_sel_hi:[1,0]
	v_pk_mul_f32 v[58:59], v[58:59], v[64:65] op_sel_hi:[1,0]
	v_pk_fma_f32 v[62:63], v[96:97], v[62:63], v[10:11]
	v_pk_fma_f32 v[68:69], v[92:93], v[58:59], v[2:3]
	s_waitcnt lgkmcnt(0)
	v_add_f32_e32 v65, v65, v70
	ds_bpermute_b32 v70, v227, v65
	v_pk_fma_f32 v[58:59], v[94:95], v[56:57], v[0:1]
	v_cvt_pk_bf16_f32 v56, v60, v61
	v_cvt_pk_bf16_f32 v57, v62, v63
	v_pk_mul_f32 v[52:53], v[52:53], v[64:65] op_sel_hi:[1,0]
	s_waitcnt lgkmcnt(0)
	v_add_f32_e32 v60, v65, v70
	ds_bpermute_b32 v61, v228, v60
	v_cvt_pk_bf16_f32 v58, v58, v59
	v_cvt_pk_bf16_f32 v59, v68, v69
	global_store_dwordx4 v[66:67], v[56:59], off sc1
	v_pk_fma_f32 v[52:53], v[90:91], v[52:53], v[12:13]
	v_pk_mul_f32 v[48:49], v[48:49], v[64:65] op_sel_hi:[1,0]
	s_waitcnt lgkmcnt(0)
	v_add_f32_e32 v56, v60, v61
	ds_bpermute_b32 v57, v229, v56
	v_pk_mul_f32 v[50:51], v[50:51], v[64:65] op_sel_hi:[1,0]
	v_pk_mul_f32 v[54:55], v[54:55], v[64:65] op_sel_hi:[1,0]
	v_or_b32_e32 v110, 4, v102
	v_pk_fma_f32 v[54:55], v[88:89], v[54:55], v[14:15]
	s_waitcnt lgkmcnt(0)
	v_add_f32_e32 v58, v56, v57
	ds_bpermute_b32 v59, v230, v58
	v_pk_fma_f32 v[56:57], v[84:85], v[50:51], v[6:7]
	v_pk_fma_f32 v[50:51], v[86:87], v[48:49], v[4:5]
	v_cvt_pk_bf16_f32 v48, v52, v53
	v_cvt_pk_bf16_f32 v49, v54, v55
	s_waitcnt lgkmcnt(0)
	v_add_f32_e32 v52, v58, v59
	v_fmamk_f32 v52, v52, 0x3a800000, v82
	v_mul_f32_e32 v53, 0x4b800000, v52
	v_cmp_gt_f32_e32 vcc, s15, v52
	v_cvt_pk_bf16_f32 v50, v50, v51
	v_cvt_pk_bf16_f32 v51, v56, v57
	global_store_dwordx4 v[66:67], v[48:51], off offset:1024 sc1
	s_waitcnt vmcnt(7)
	v_mov_b32_e32 v54, v29
	v_cndmask_b32_e32 v52, v52, v53, vcc
	v_rsq_f32_e32 v52, v52
	s_waitcnt vmcnt(6)
	v_mov_b32_e32 v55, v25
	v_mov_b32_e32 v53, v24
	v_pk_mul_f32 v[54:55], v[54:55], v[54:55]
	v_mul_f32_e32 v48, 0x45800000, v52
	v_cndmask_b32_e32 v48, v52, v48, vcc
	v_mov_b32_e32 v52, v28
	v_pk_fma_f32 v[52:53], v[52:53], v[52:53], v[54:55]
	v_mov_b32_e32 v54, v30
	v_mov_b32_e32 v55, v26
	v_pk_fma_f32 v[52:53], v[54:55], v[54:55], v[52:53]
	v_mov_b32_e32 v54, v31
	v_mov_b32_e32 v55, v27
	s_waitcnt vmcnt(5)
	v_mov_b32_e32 v56, v21
	s_waitcnt vmcnt(4)
	v_mov_b32_e32 v57, v17
	v_pk_fma_f32 v[52:53], v[54:55], v[54:55], v[52:53]
	v_mov_b32_e32 v54, v20
	v_mov_b32_e32 v55, v16
	v_pk_mul_f32 v[56:57], v[56:57], v[56:57]
	v_add_f32_e32 v49, v52, v53
	v_pk_fma_f32 v[54:55], v[54:55], v[54:55], v[56:57]
	v_mov_b32_e32 v56, v22
	v_mov_b32_e32 v57, v18
	v_pk_fma_f32 v[54:55], v[56:57], v[56:57], v[54:55]
	v_mov_b32_e32 v56, v23
	v_mov_b32_e32 v57, v19
	v_pk_fma_f32 v[54:55], v[56:57], v[56:57], v[54:55]
	v_lshlrev_b64 v[50:51], 11, v[108:109]
	v_add_f32_e32 v49, v49, v54
	v_add_f32_e32 v49, v49, v55
	ds_bpermute_b32 v52, v225, v49
	v_pk_mul_f32 v[44:45], v[44:45], v[48:49] op_sel_hi:[1,0]
	v_pk_mul_f32 v[46:47], v[46:47], v[48:49] op_sel_hi:[1,0]
	v_pk_fma_f32 v[44:45], v[98:99], v[44:45], v[8:9]
	v_lshl_add_u64 v[50:51], v[100:101], 0, v[50:51]
	s_waitcnt lgkmcnt(0)
	v_add_f32_e32 v49, v49, v52
	ds_bpermute_b32 v54, v226, v49
	v_pk_mul_f32 v[40:41], v[40:41], v[48:49] op_sel_hi:[1,0]
	v_pk_mul_f32 v[42:43], v[42:43], v[48:49] op_sel_hi:[1,0]
	v_pk_fma_f32 v[46:47], v[96:97], v[46:47], v[10:11]
	v_pk_fma_f32 v[52:53], v[92:93], v[42:43], v[2:3]
	s_waitcnt lgkmcnt(0)
	v_add_f32_e32 v49, v49, v54
	ds_bpermute_b32 v54, v227, v49
	v_pk_fma_f32 v[42:43], v[94:95], v[40:41], v[0:1]
	v_cvt_pk_bf16_f32 v40, v44, v45
	v_cvt_pk_bf16_f32 v41, v46, v47
	v_pk_mul_f32 v[36:37], v[36:37], v[48:49] op_sel_hi:[1,0]
	s_waitcnt lgkmcnt(0)
	v_add_f32_e32 v44, v49, v54
	ds_bpermute_b32 v45, v228, v44
	v_cvt_pk_bf16_f32 v42, v42, v43
	v_cvt_pk_bf16_f32 v43, v52, v53
	global_store_dwordx4 v[50:51], v[40:43], off sc1
	v_pk_fma_f32 v[36:37], v[90:91], v[36:37], v[12:13]
	v_pk_mul_f32 v[32:33], v[32:33], v[48:49] op_sel_hi:[1,0]
	s_waitcnt lgkmcnt(0)
	v_add_f32_e32 v40, v44, v45
	ds_bpermute_b32 v41, v229, v40
	v_pk_mul_f32 v[34:35], v[34:35], v[48:49] op_sel_hi:[1,0]
	v_pk_mul_f32 v[38:39], v[38:39], v[48:49] op_sel_hi:[1,0]
	v_ashrrev_i32_e32 v111, 31, v110
	v_pk_fma_f32 v[38:39], v[88:89], v[38:39], v[14:15]
	s_waitcnt lgkmcnt(0)
	v_add_f32_e32 v42, v40, v41
	ds_bpermute_b32 v43, v230, v42
	v_pk_fma_f32 v[40:41], v[84:85], v[34:35], v[6:7]
	v_pk_fma_f32 v[34:35], v[86:87], v[32:33], v[4:5]
	v_cvt_pk_bf16_f32 v32, v36, v37
	v_cvt_pk_bf16_f32 v33, v38, v39
	s_waitcnt lgkmcnt(0)
; __device__ __forceinline__ void st_bf16x8(bf16_t* p, const f32x4 a, const f32x4 b) { uint4 o; o.x = cvt_pk_bf16(a[0], a[1]); o.y = cvt_pk_bf16(a[2], a[3]); o.z = cvt_pk_bf16(b[0], b[1]); o.w = cvt_pk_bf16(b[2], b[3]); *(uint4*)p = o; }
; __device__ __forceinline__ void p1_prompt_rows(const Params& p) {
;     ...
;     for (int trip = 0; trip < 2; ++trip) { const int rowb = gw * 8 + trip * 4;
;         f32x4 v[4][4];
; #pragma unroll
;         for (int q = 0; q < 4; ++q)
; #pragma unroll
;             for (int i = 0; i < 4; ++i) v[q][i] = *(const f32x4*)(p.x_prompt + (size_t)(rowb + q) * DM + (i >> 1) * 512 + lane * 8 + (i & 1) * 4);
;         __builtin_amdgcn_sched_barrier(0);
; #pragma unroll
;         for (int q = 0; q < 4; ++q) { float ss = 0.f;
; #pragma unroll
;             for (int i = 0; i < 4; ++i) ss += v[q][i][0] * v[q][i][0] + v[q][i][1] * v[q][i][1] + v[q][i][2] * v[q][i][2] + v[q][i][3] * v[q][i][3];
; #pragma unroll
;             for (int o = 1; o < 64; o <<= 1) ss += __shfl_xor(ss, o);
;             const float rs = rsqrtf(ss * (1.f / DM) + EPS);
; #pragma unroll
;             for (int h = 0; h < 2; ++h) st_bf16x8(H + (size_t)(rowb + q) * DM + h * 512 + lane * 8, v[q][2 * h] * rs * gs[2 * h] + sh[2 * h], v[q][2 * h + 1] * rs * gs[2 * h + 1] + sh[2 * h + 1]); }
	v_add_f32_e32 v36, v42, v43
	v_fmamk_f32 v36, v36, 0x3a800000, v82
	v_mul_f32_e32 v37, 0x4b800000, v36
	v_cmp_gt_f32_e32 vcc, s15, v36
	v_cvt_pk_bf16_f32 v34, v34, v35
	v_cvt_pk_bf16_f32 v35, v40, v41
	global_store_dwordx4 v[50:51], v[32:35], off offset:1024 sc1
	v_or_b32_e32 v112, 5, v102
	v_cndmask_b32_e32 v36, v36, v37, vcc
	v_rsq_f32_e32 v36, v36
	v_lshlrev_b64 v[34:35], 11, v[106:107]
	v_lshl_add_u64 v[34:35], v[100:101], 0, v[34:35]
	v_ashrrev_i32_e32 v113, 31, v112
	v_mul_f32_e32 v32, 0x45800000, v36
	v_cndmask_b32_e32 v32, v36, v32, vcc
	v_pk_mul_f32 v[28:29], v[28:29], v[32:33] op_sel_hi:[1,0]
	v_pk_mul_f32 v[30:31], v[30:31], v[32:33] op_sel_hi:[1,0]
	v_pk_mul_f32 v[24:25], v[24:25], v[32:33] op_sel_hi:[1,0]
	v_pk_mul_f32 v[26:27], v[26:27], v[32:33] op_sel_hi:[1,0]
	v_pk_fma_f32 v[30:31], v[96:97], v[30:31], v[10:11]
	v_pk_fma_f32 v[28:29], v[98:99], v[28:29], v[8:9]
	v_pk_fma_f32 v[36:37], v[92:93], v[26:27], v[2:3]
	v_pk_fma_f32 v[26:27], v[94:95], v[24:25], v[0:1]
	v_cvt_pk_bf16_f32 v24, v28, v29
	v_cvt_pk_bf16_f32 v25, v30, v31
	v_pk_mul_f32 v[20:21], v[20:21], v[32:33] op_sel_hi:[1,0]
	v_pk_mul_f32 v[22:23], v[22:23], v[32:33] op_sel_hi:[1,0]
	v_pk_mul_f32 v[16:17], v[16:17], v[32:33] op_sel_hi:[1,0]
	v_pk_mul_f32 v[18:19], v[18:19], v[32:33] op_sel_hi:[1,0]
	v_cvt_pk_bf16_f32 v26, v26, v27
	v_cvt_pk_bf16_f32 v27, v36, v37
	global_store_dwordx4 v[34:35], v[24:27], off sc1
	v_pk_fma_f32 v[22:23], v[88:89], v[22:23], v[14:15]
	v_pk_fma_f32 v[20:21], v[90:91], v[20:21], v[12:13]
	v_pk_fma_f32 v[24:25], v[84:85], v[18:19], v[6:7]
	v_pk_fma_f32 v[18:19], v[86:87], v[16:17], v[4:5]
	v_cvt_pk_bf16_f32 v16, v20, v21
	v_cvt_pk_bf16_f32 v17, v22, v23
	v_or_b32_e32 v66, 6, v102
	v_cvt_pk_bf16_f32 v18, v18, v19
	v_cvt_pk_bf16_f32 v19, v24, v25
	global_store_dwordx4 v[34:35], v[16:19], off offset:1024 sc1
	v_ashrrev_i32_e32 v67, 31, v66
	v_or_b32_e32 v64, 7, v102
	v_lshlrev_b64 v[16:17], 12, v[110:111]
	v_lshl_add_u64 v[16:17], v[104:105], 0, v[16:17]
	global_load_dwordx4 v[68:71], v[16:17], off nt
	global_load_dwordx4 v[72:75], v[16:17], off offset:16 nt
	global_load_dwordx4 v[76:79], v[16:17], off offset:2048 nt
	global_load_dwordx4 v[106:109], v[16:17], off offset:2064 nt
	v_lshlrev_b64 v[16:17], 12, v[112:113]
	v_lshl_add_u64 v[16:17], v[104:105], 0, v[16:17]
	global_load_dwordx4 v[60:63], v[16:17], off nt
	global_load_dwordx4 v[56:59], v[16:17], off offset:16 nt
	global_load_dwordx4 v[52:55], v[16:17], off offset:2048 nt
	global_load_dwordx4 v[48:51], v[16:17], off offset:2064 nt
	v_lshlrev_b64 v[16:17], 12, v[66:67]
	v_lshl_add_u64 v[16:17], v[104:105], 0, v[16:17]
	v_ashrrev_i32_e32 v65, 31, v64
	global_load_dwordx4 v[44:47], v[16:17], off nt
	global_load_dwordx4 v[40:43], v[16:17], off offset:16 nt
	global_load_dwordx4 v[36:39], v[16:17], off offset:2048 nt
	global_load_dwordx4 v[32:35], v[16:17], off offset:2064 nt
	v_lshlrev_b64 v[16:17], 12, v[64:65]
	v_lshl_add_u64 v[16:17], v[104:105], 0, v[16:17]
	global_load_dwordx4 v[28:31], v[16:17], off nt
	global_load_dwordx4 v[24:27], v[16:17], off offset:16 nt
	global_load_dwordx4 v[20:23], v[16:17], off offset:2048 nt
	s_nop 0
	global_load_dwordx4 v[16:19], v[16:17], off offset:2064 nt
	s_waitcnt vmcnt(15)
	v_mov_b32_e32 v104, v69
	s_waitcnt vmcnt(14)
	v_mov_b32_e32 v105, v73
	v_mov_b32_e32 v102, v68
	v_mov_b32_e32 v103, v72
	v_pk_mul_f32 v[104:105], v[104:105], v[104:105]
	s_waitcnt vmcnt(13)
	v_mov_b32_e32 v114, v77
	v_pk_fma_f32 v[102:103], v[102:103], v[102:103], v[104:105]
	v_mov_b32_e32 v104, v70
	v_mov_b32_e32 v105, v74
	v_pk_fma_f32 v[102:103], v[104:105], v[104:105], v[102:103]
	v_mov_b32_e32 v104, v71
	v_mov_b32_e32 v105, v75
	s_waitcnt vmcnt(12)
	v_mov_b32_e32 v115, v107
	v_pk_fma_f32 v[102:103], v[104:105], v[104:105], v[102:103]
	v_mov_b32_e32 v104, v76
	v_mov_b32_e32 v105, v106
	v_pk_mul_f32 v[114:115], v[114:115], v[114:115]
	v_add_f32_e32 v80, v102, v103
	v_pk_fma_f32 v[104:105], v[104:105], v[104:105], v[114:115]
	v_mov_b32_e32 v114, v78
	v_mov_b32_e32 v115, v108
	v_pk_fma_f32 v[104:105], v[114:115], v[114:115], v[104:105]
	v_mov_b32_e32 v114, v79
	v_mov_b32_e32 v115, v109
	v_pk_fma_f32 v[104:105], v[114:115], v[114:115], v[104:105]
	v_lshlrev_b64 v[102:103], 11, v[110:111]
	v_add_f32_e32 v80, v80, v104
	v_add_f32_e32 v80, v80, v105
	ds_bpermute_b32 v83, v225, v80
	s_waitcnt vmcnt(11)
	v_mov_b32_e32 v110, v61
	s_waitcnt vmcnt(10)
	v_mov_b32_e32 v111, v57
	v_mov_b32_e32 v104, v60
	v_mov_b32_e32 v105, v56
	s_waitcnt lgkmcnt(0)
	v_add_f32_e32 v80, v80, v83
	ds_bpermute_b32 v83, v226, v80
	v_pk_mul_f32 v[110:111], v[110:111], v[110:111]
	s_waitcnt vmcnt(9)
	v_mov_b32_e32 v114, v53
	v_pk_fma_f32 v[104:105], v[104:105], v[104:105], v[110:111]
	v_mov_b32_e32 v110, v62
	s_waitcnt lgkmcnt(0)
	v_add_f32_e32 v80, v80, v83
	ds_bpermute_b32 v83, v227, v80
	v_mov_b32_e32 v111, v58
	v_pk_fma_f32 v[104:105], v[110:111], v[110:111], v[104:105]
	v_mov_b32_e32 v110, v63
	v_mov_b32_e32 v111, v59
	s_waitcnt lgkmcnt(0)
	v_add_f32_e32 v80, v80, v83
	ds_bpermute_b32 v83, v228, v80
	s_waitcnt vmcnt(8)
	v_mov_b32_e32 v115, v49
	v_pk_fma_f32 v[104:105], v[110:111], v[110:111], v[104:105]
	v_mov_b32_e32 v110, v52
	v_mov_b32_e32 v111, v48
	s_waitcnt lgkmcnt(0)
	v_add_f32_e32 v80, v80, v83
	ds_bpermute_b32 v83, v229, v80
	v_pk_mul_f32 v[114:115], v[114:115], v[114:115]
	v_lshl_add_u64 v[102:103], v[100:101], 0, v[102:103]
	v_pk_fma_f32 v[110:111], v[110:111], v[110:111], v[114:115]
	v_mov_b32_e32 v114, v54
	s_waitcnt lgkmcnt(0)
	v_add_f32_e32 v80, v80, v83
	ds_bpermute_b32 v83, v230, v80
	v_mov_b32_e32 v115, v50
	v_pk_fma_f32 v[110:111], v[114:115], v[114:115], v[110:111]
	v_mov_b32_e32 v114, v55
	v_mov_b32_e32 v115, v51
	s_waitcnt lgkmcnt(0)
; __device__ __forceinline__ void st_bf16x8(bf16_t* p, const f32x4 a, const f32x4 b) { uint4 o; o.x = cvt_pk_bf16(a[0], a[1]); o.y = cvt_pk_bf16(a[2], a[3]); o.z = cvt_pk_bf16(b[0], b[1]); o.w = cvt_pk_bf16(b[2], b[3]); *(uint4*)p = o; }
; __device__ __forceinline__ void p1_prompt_rows(const Params& p) {
;     ...
;         for (int q = 0; q < 4; ++q) { float ss = 0.f;
; #pragma unroll
;             for (int i = 0; i < 4; ++i) ss += v[q][i][0] * v[q][i][0] + v[q][i][1] * v[q][i][1] + v[q][i][2] * v[q][i][2] + v[q][i][3] * v[q][i][3];
; #pragma unroll
;             for (int o = 1; o < 64; o <<= 1) ss += __shfl_xor(ss, o);
;             const float rs = rsqrtf(ss * (1.f / DM) + EPS);
; #pragma unroll
;             for (int h = 0; h < 2; ++h) st_bf16x8(H + (size_t)(rowb + q) * DM + h * 512 + lane * 8, v[q][2 * h] * rs * gs[2 * h] + sh[2 * h], v[q][2 * h + 1] * rs * gs[2 * h + 1] + sh[2 * h + 1]); }
	v_add_f32_e32 v80, v80, v83
	v_fmamk_f32 v80, v80, 0x3a800000, v82
	v_mul_f32_e32 v83, 0x4b800000, v80
	v_cmp_gt_f32_e32 vcc, s15, v80
	v_pk_fma_f32 v[110:111], v[114:115], v[114:115], v[110:111]
	s_movk_i32 s33, 0x4080
	v_cndmask_b32_e32 v80, v80, v83, vcc
	v_rsq_f32_e32 v80, v80
	s_nop 0
	v_mul_f32_e32 v83, 0x45800000, v80
	v_cndmask_b32_e32 v80, v80, v83, vcc
	v_add_f32_e32 v83, v104, v105
	v_add_f32_e32 v83, v83, v110
	v_add_f32_e32 v83, v83, v111
	ds_bpermute_b32 v104, v225, v83
	v_pk_mul_f32 v[68:69], v[68:69], v[80:81] op_sel_hi:[1,0]
	v_pk_mul_f32 v[70:71], v[70:71], v[80:81] op_sel_hi:[1,0]
	v_pk_mul_f32 v[72:73], v[72:73], v[80:81] op_sel_hi:[1,0]
	v_pk_fma_f32 v[70:71], v[96:97], v[70:71], v[10:11]
	s_waitcnt lgkmcnt(0)
	v_add_f32_e32 v83, v83, v104
	ds_bpermute_b32 v104, v226, v83
	v_pk_fma_f32 v[68:69], v[98:99], v[68:69], v[8:9]
	v_pk_fma_f32 v[72:73], v[94:95], v[72:73], v[0:1]
	v_cvt_pk_bf16_f32 v68, v68, v69
	v_cvt_pk_bf16_f32 v69, v70, v71
	s_waitcnt lgkmcnt(0)
	v_add_f32_e32 v83, v83, v104
	ds_bpermute_b32 v104, v227, v83
	v_cvt_pk_bf16_f32 v70, v72, v73
	v_pk_mul_f32 v[74:75], v[74:75], v[80:81] op_sel_hi:[1,0]
	s_waitcnt lgkmcnt(0)
	v_add_f32_e32 v72, v83, v104
	ds_bpermute_b32 v73, v228, v72
	v_pk_fma_f32 v[74:75], v[92:93], v[74:75], v[2:3]
	s_nop 0
	v_cvt_pk_bf16_f32 v71, v74, v75
	global_store_dwordx4 v[102:103], v[68:71], off sc1
	v_pk_mul_f32 v[74:75], v[108:109], v[80:81] op_sel_hi:[1,0]
	s_nop 0
	v_pk_mul_f32 v[68:69], v[76:77], v[80:81] op_sel_hi:[1,0]
	s_waitcnt lgkmcnt(0)
	v_add_f32_e32 v76, v72, v73
	ds_bpermute_b32 v77, v229, v76
	v_pk_mul_f32 v[70:71], v[78:79], v[80:81] op_sel_hi:[1,0]
	v_pk_fma_f32 v[68:69], v[90:91], v[68:69], v[12:13]
	v_pk_fma_f32 v[70:71], v[88:89], v[70:71], v[14:15]
	v_cvt_pk_bf16_f32 v68, v68, v69
	s_waitcnt lgkmcnt(0)
	v_add_f32_e32 v76, v76, v77
	ds_bpermute_b32 v77, v230, v76
	v_cvt_pk_bf16_f32 v69, v70, v71
	v_pk_mul_f32 v[72:73], v[106:107], v[80:81] op_sel_hi:[1,0]
	v_pk_fma_f32 v[74:75], v[84:85], v[74:75], v[6:7]
	v_pk_fma_f32 v[72:73], v[86:87], v[72:73], v[4:5]
	s_waitcnt lgkmcnt(0)
	v_add_f32_e32 v70, v76, v77
	v_fmamk_f32 v70, v70, 0x3a800000, v82
	v_mul_f32_e32 v71, 0x4b800000, v70
	v_cmp_gt_f32_e32 vcc, s15, v70
	s_waitcnt vmcnt(5)
	v_mov_b32_e32 v77, v33
	v_cndmask_b32_e32 v70, v70, v71, vcc
	v_rsq_f32_e32 v76, v70
	v_cvt_pk_bf16_f32 v71, v74, v75
	v_mov_b32_e32 v74, v45
	v_mov_b32_e32 v75, v41
	v_cvt_pk_bf16_f32 v70, v72, v73
	v_mov_b32_e32 v72, v44
	v_mov_b32_e32 v73, v40
	v_pk_mul_f32 v[74:75], v[74:75], v[74:75]
	global_store_dwordx4 v[102:103], v[68:71], off offset:1024 sc1
	v_pk_fma_f32 v[72:73], v[72:73], v[72:73], v[74:75]
	v_mov_b32_e32 v74, v46
	v_mul_f32_e32 v68, 0x45800000, v76
	v_mov_b32_e32 v75, v42
	v_cndmask_b32_e32 v68, v76, v68, vcc
	v_pk_fma_f32 v[72:73], v[74:75], v[74:75], v[72:73]
	v_mov_b32_e32 v74, v47
	v_mov_b32_e32 v75, v43
	v_mov_b32_e32 v76, v37
	v_pk_fma_f32 v[72:73], v[74:75], v[74:75], v[72:73]
	v_mov_b32_e32 v74, v36
	v_mov_b32_e32 v75, v32
	v_pk_mul_f32 v[76:77], v[76:77], v[76:77]
	v_add_f32_e32 v69, v72, v73
	v_pk_fma_f32 v[74:75], v[74:75], v[74:75], v[76:77]
	v_mov_b32_e32 v76, v38
	v_mov_b32_e32 v77, v34
	v_pk_fma_f32 v[74:75], v[76:77], v[76:77], v[74:75]
	v_mov_b32_e32 v76, v39
	v_mov_b32_e32 v77, v35
	v_pk_fma_f32 v[74:75], v[76:77], v[76:77], v[74:75]
	v_lshlrev_b64 v[70:71], 11, v[112:113]
	v_add_f32_e32 v69, v69, v74
	v_add_f32_e32 v69, v69, v75
	ds_bpermute_b32 v72, v225, v69
	v_pk_mul_f32 v[60:61], v[60:61], v[68:69] op_sel_hi:[1,0]
	v_pk_mul_f32 v[62:63], v[62:63], v[68:69] op_sel_hi:[1,0]
	v_pk_fma_f32 v[60:61], v[98:99], v[60:61], v[8:9]
	v_lshl_add_u64 v[70:71], v[100:101], 0, v[70:71]
	s_waitcnt lgkmcnt(0)
	v_add_f32_e32 v69, v69, v72
	ds_bpermute_b32 v74, v226, v69
	v_pk_mul_f32 v[56:57], v[56:57], v[68:69] op_sel_hi:[1,0]
	v_pk_mul_f32 v[58:59], v[58:59], v[68:69] op_sel_hi:[1,0]
	v_pk_fma_f32 v[62:63], v[96:97], v[62:63], v[10:11]
	v_pk_fma_f32 v[72:73], v[92:93], v[58:59], v[2:3]
	s_waitcnt lgkmcnt(0)
	v_add_f32_e32 v69, v69, v74
	ds_bpermute_b32 v74, v227, v69
	v_pk_fma_f32 v[58:59], v[94:95], v[56:57], v[0:1]
	v_cvt_pk_bf16_f32 v56, v60, v61
	v_cvt_pk_bf16_f32 v57, v62, v63
	v_pk_mul_f32 v[52:53], v[52:53], v[68:69] op_sel_hi:[1,0]
	s_waitcnt lgkmcnt(0)
	v_add_f32_e32 v60, v69, v74
	ds_bpermute_b32 v61, v228, v60
	v_cvt_pk_bf16_f32 v58, v58, v59
	v_cvt_pk_bf16_f32 v59, v72, v73
	global_store_dwordx4 v[70:71], v[56:59], off sc1
	v_pk_fma_f32 v[52:53], v[90:91], v[52:53], v[12:13]
	v_pk_mul_f32 v[48:49], v[48:49], v[68:69] op_sel_hi:[1,0]
	s_waitcnt lgkmcnt(0)
	v_add_f32_e32 v56, v60, v61
	ds_bpermute_b32 v57, v229, v56
	v_pk_mul_f32 v[50:51], v[50:51], v[68:69] op_sel_hi:[1,0]
	v_pk_mul_f32 v[54:55], v[54:55], v[68:69] op_sel_hi:[1,0]
	s_waitcnt lgkmcnt(0)
	v_add_f32_e32 v58, v56, v57
	ds_bpermute_b32 v59, v230, v58
	v_pk_fma_f32 v[56:57], v[84:85], v[50:51], v[6:7]
	v_pk_fma_f32 v[50:51], v[86:87], v[48:49], v[4:5]
	v_cvt_pk_bf16_f32 v48, v52, v53
	v_pk_fma_f32 v[54:55], v[88:89], v[54:55], v[14:15]
	s_waitcnt lgkmcnt(0)
	v_add_f32_e32 v52, v58, v59
	v_fmamk_f32 v52, v52, 0x3a800000, v82
	v_mul_f32_e32 v53, 0x4b800000, v52
	v_cmp_gt_f32_e32 vcc, s15, v52
	v_cvt_pk_bf16_f32 v49, v54, v55
	v_cvt_pk_bf16_f32 v50, v50, v51
	v_cvt_pk_bf16_f32 v51, v56, v57
	global_store_dwordx4 v[70:71], v[48:51], off offset:1024 sc1
	s_waitcnt vmcnt(7)
	v_mov_b32_e32 v54, v29
	v_cndmask_b32_e32 v52, v52, v53, vcc
	v_rsq_f32_e32 v52, v52
	s_waitcnt vmcnt(6)
; __device__ __forceinline__ int fresh_tid() { int t = threadIdx.x; asm volatile("" : "+v"(t)); return t; }
; __device__ __forceinline__ void st_bf16x8(bf16_t* p, const f32x4 a, const f32x4 b) { uint4 o; o.x = cvt_pk_bf16(a[0], a[1]); o.y = cvt_pk_bf16(a[2], a[3]); o.z = cvt_pk_bf16(b[0], b[1]); o.w = cvt_pk_bf16(b[2], b[3]); *(uint4*)p = o; }
;     const int tid = fresh_tid(), lane = tid & 63, gw = blockIdx.x * 8 + (tid >> 6), nw = (nblk ? nblk : (int)gridDim.x) * 8;
;     const float* mod = (const float*)(p.ws + WS_MOD); bf16_t* H = (bf16_t*)(p.ws + WS_H);
;     f32x4 gv[4];
; #pragma unroll
;     for (int i = 0; i < 4; ++i) gv[i] = *(const f32x4*)(g + (i >> 1) * 512 + lane * 8 + (i & 1) * 4);
;     for (int rowb = r0 + gw; rowb < r1; rowb += 4 * nw) {
;         f32x4 v[4][4];
; #pragma unroll
;         for (int q = 0; q < 4; ++q) { const int row = rowb + q * nw;
;             if (row < r1) { const float* src = from_out ? p.out + (size_t)row * DM : (row < NP ? p.x_prompt + (size_t)row * DM : p.x_sample + (size_t)(row - NP) * DM);
; #pragma unroll
;                 for (int i = 0; i < 4; ++i) v[q][i] = *(const f32x4*)(src + (i >> 1) * 512 + lane * 8 + (i & 1) * 4); }
; __device__ __forceinline__ void p1_prompt_rows(const Params& p) {
;     ...
;             const float rs = rsqrtf(ss * (1.f / DM) + EPS);
; #pragma unroll
;             for (int h = 0; h < 2; ++h) st_bf16x8(H + (size_t)(rowb + q) * DM + h * 512 + lane * 8, v[q][2 * h] * rs * gs[2 * h] + sh[2 * h], v[q][2 * h + 1] * rs * gs[2 * h + 1] + sh[2 * h + 1]); }
	v_mov_b32_e32 v55, v25
	v_mov_b32_e32 v53, v24
	v_pk_mul_f32 v[54:55], v[54:55], v[54:55]
	v_mul_f32_e32 v48, 0x45800000, v52
	v_cndmask_b32_e32 v48, v52, v48, vcc
	v_mov_b32_e32 v52, v28
	v_pk_fma_f32 v[52:53], v[52:53], v[52:53], v[54:55]
	v_mov_b32_e32 v54, v30
	v_mov_b32_e32 v55, v26
	v_pk_fma_f32 v[52:53], v[54:55], v[54:55], v[52:53]
	v_mov_b32_e32 v54, v31
	v_mov_b32_e32 v55, v27
	s_waitcnt vmcnt(5)
	v_mov_b32_e32 v56, v21
	s_waitcnt vmcnt(4)
	v_mov_b32_e32 v57, v17
	v_pk_fma_f32 v[52:53], v[54:55], v[54:55], v[52:53]
	v_mov_b32_e32 v54, v20
	v_mov_b32_e32 v55, v16
	v_pk_mul_f32 v[56:57], v[56:57], v[56:57]
	v_add_f32_e32 v49, v52, v53
	v_pk_fma_f32 v[54:55], v[54:55], v[54:55], v[56:57]
	v_mov_b32_e32 v56, v22
	v_mov_b32_e32 v57, v18
	v_pk_fma_f32 v[54:55], v[56:57], v[56:57], v[54:55]
	v_mov_b32_e32 v56, v23
	v_mov_b32_e32 v57, v19
	v_pk_fma_f32 v[54:55], v[56:57], v[56:57], v[54:55]
	v_lshlrev_b64 v[50:51], 11, v[66:67]
	v_add_f32_e32 v49, v49, v54
	v_add_f32_e32 v49, v49, v55
	ds_bpermute_b32 v52, v225, v49
	v_pk_mul_f32 v[44:45], v[44:45], v[48:49] op_sel_hi:[1,0]
	v_pk_mul_f32 v[46:47], v[46:47], v[48:49] op_sel_hi:[1,0]
	v_pk_fma_f32 v[44:45], v[98:99], v[44:45], v[8:9]
	v_lshl_add_u64 v[50:51], v[100:101], 0, v[50:51]
	s_waitcnt lgkmcnt(0)
	v_add_f32_e32 v49, v49, v52
	ds_bpermute_b32 v54, v226, v49
	v_pk_mul_f32 v[40:41], v[40:41], v[48:49] op_sel_hi:[1,0]
	v_pk_mul_f32 v[42:43], v[42:43], v[48:49] op_sel_hi:[1,0]
	v_pk_fma_f32 v[46:47], v[96:97], v[46:47], v[10:11]
	v_pk_fma_f32 v[52:53], v[92:93], v[42:43], v[2:3]
	s_waitcnt lgkmcnt(0)
	v_add_f32_e32 v49, v49, v54
	ds_bpermute_b32 v54, v227, v49
	v_pk_fma_f32 v[42:43], v[94:95], v[40:41], v[0:1]
	v_cvt_pk_bf16_f32 v40, v44, v45
	v_cvt_pk_bf16_f32 v41, v46, v47
	v_pk_mul_f32 v[36:37], v[36:37], v[48:49] op_sel_hi:[1,0]
	s_waitcnt lgkmcnt(0)
	v_add_f32_e32 v44, v49, v54
	ds_bpermute_b32 v45, v228, v44
	v_cvt_pk_bf16_f32 v42, v42, v43
	v_cvt_pk_bf16_f32 v43, v52, v53
	global_store_dwordx4 v[50:51], v[40:43], off sc1
	v_pk_fma_f32 v[36:37], v[90:91], v[36:37], v[12:13]
	v_pk_mul_f32 v[32:33], v[32:33], v[48:49] op_sel_hi:[1,0]
	s_waitcnt lgkmcnt(0)
	v_add_f32_e32 v40, v44, v45
	ds_bpermute_b32 v41, v229, v40
	v_pk_mul_f32 v[34:35], v[34:35], v[48:49] op_sel_hi:[1,0]
	v_pk_mul_f32 v[38:39], v[38:39], v[48:49] op_sel_hi:[1,0]
	s_waitcnt lgkmcnt(0)
	v_add_f32_e32 v42, v40, v41
	ds_bpermute_b32 v43, v230, v42
	v_pk_fma_f32 v[40:41], v[84:85], v[34:35], v[6:7]
	v_pk_fma_f32 v[34:35], v[86:87], v[32:33], v[4:5]
	v_cvt_pk_bf16_f32 v32, v36, v37
	v_pk_fma_f32 v[38:39], v[88:89], v[38:39], v[14:15]
	s_waitcnt lgkmcnt(0)
	v_add_f32_e32 v36, v42, v43
	v_fmamk_f32 v36, v36, 0x3a800000, v82
	v_mul_f32_e32 v37, 0x4b800000, v36
	v_cmp_gt_f32_e32 vcc, s15, v36
	v_cvt_pk_bf16_f32 v33, v38, v39
	v_cvt_pk_bf16_f32 v34, v34, v35
	v_cvt_pk_bf16_f32 v35, v40, v41
	global_store_dwordx4 v[50:51], v[32:35], off offset:1024 sc1
	s_nop 0
	v_cndmask_b32_e32 v36, v36, v37, vcc
	v_rsq_f32_e32 v36, v36
	v_lshlrev_b64 v[34:35], 11, v[64:65]
	v_lshl_add_u64 v[34:35], v[100:101], 0, v[34:35]
	v_mul_f32_e32 v32, 0x45800000, v36
	v_cndmask_b32_e32 v32, v36, v32, vcc
	v_pk_mul_f32 v[24:25], v[24:25], v[32:33] op_sel_hi:[1,0]
	v_pk_mul_f32 v[26:27], v[26:27], v[32:33] op_sel_hi:[1,0]
	v_pk_mul_f32 v[28:29], v[28:29], v[32:33] op_sel_hi:[1,0]
	v_pk_mul_f32 v[30:31], v[30:31], v[32:33] op_sel_hi:[1,0]
	v_pk_fma_f32 v[26:27], v[92:93], v[26:27], v[2:3]
	v_pk_fma_f32 v[2:3], v[94:95], v[24:25], v[0:1]
	v_pk_fma_f32 v[10:11], v[96:97], v[30:31], v[10:11]
	v_pk_fma_f32 v[8:9], v[98:99], v[28:29], v[8:9]
	v_cvt_pk_bf16_f32 v1, v10, v11
	v_cvt_pk_bf16_f32 v2, v2, v3
	v_cvt_pk_bf16_f32 v3, v26, v27
	v_pk_mul_f32 v[10:11], v[18:19], v[32:33] op_sel_hi:[1,0]
	v_cvt_pk_bf16_f32 v0, v8, v9
	global_store_dwordx4 v[34:35], v[0:3], off sc1
	v_pk_mul_f32 v[8:9], v[16:17], v[32:33] op_sel_hi:[1,0]
	v_mov_b32_e32 v17, v224
	v_pk_mul_f32 v[0:1], v[20:21], v[32:33] op_sel_hi:[1,0]
	v_pk_mul_f32 v[2:3], v[22:23], v[32:33] op_sel_hi:[1,0]
	v_pk_fma_f32 v[0:1], v[90:91], v[0:1], v[12:13]
	v_pk_fma_f32 v[2:3], v[88:89], v[2:3], v[14:15]
	v_pk_fma_f32 v[6:7], v[84:85], v[10:11], v[6:7]
	v_pk_fma_f32 v[4:5], v[86:87], v[8:9], v[4:5]
	v_cvt_pk_bf16_f32 v0, v0, v1
	v_cvt_pk_bf16_f32 v1, v2, v3
	v_cvt_pk_bf16_f32 v3, v6, v7
	s_nop 0
	v_cvt_pk_bf16_f32 v2, v4, v5
	global_store_dwordx4 v[34:35], v[0:3], off offset:1024 sc1
	s_nop 0
	v_ashrrev_i32_e32 v16, 6, v17
	v_add_u32_e32 v64, s97, v16
	v_cmp_gt_i32_e32 vcc, s33, v64
	s_and_saveexec_b64 s[30:31], vcc
	s_cbranch_execz .LBB0_148
	v_lshlrev_b32_e32 v0, 3, v17
	v_and_b32_e32 v66, 0x1f8, v0
	v_lshlrev_b32_e32 v12, 2, v66
	global_load_dwordx4 v[0:3], v12, s[46:47] offset:16
	global_load_dwordx4 v[4:7], v12, s[46:47]
	global_load_dwordx4 v[8:11], v12, s[46:47] offset:2064
	s_nop 0
	global_load_dwordx4 v[12:15], v12, s[46:47] offset:2048
	s_add_i32 s0, s94, s95
	v_add_u32_e32 v16, s0, v16
	v_add_u32_e32 v72, 0x4000, v16
	v_and_b32_e32 v17, 63, v17
	v_ashrrev_i32_e32 v73, 31, v72
	s_lshl_b32 s46, s34, 5
	v_lshlrev_b32_e32 v70, 4, v17
	v_lshlrev_b64 v[16:17], 11, v[72:73]
	v_ashrrev_i32_e32 v65, 31, v64
	v_or_b32_e32 v18, 0x200, v66
	v_lshlrev_b32_e32 v80, 1, v66
	v_lshl_add_u64 v[74:75], s[58:59], 0, v[16:17]
	s_ashr_i32 s47, s46, 31
	v_lshlrev_b64 v[16:17], 11, v[64:65]
	v_lshl_add_u64 v[68:69], s[26:27], 0, v[80:81]
	s_lshl_b32 s60, s34, 4
	s_mul_i32 s61, s34, 24
	v_mov_b32_e32 v71, v81
	s_lshl_b64 s[48:49], s[46:47], 11
	v_lshl_add_u64 v[76:77], s[58:59], 0, v[16:17]
	s_mov_b64 s[50:51], 0
	s_mov_b32 s66, 0x1a70000
	v_lshlrev_b32_e32 v78, 2, v18
	s_movk_i32 s67, 0x407f
	s_mov_b64 s[52:53], 0
	v_mov_b32_e32 v67, v64
	s_branch .LBB0_136

;     ...
;         for (int q = 0; q < 4; ++q) { const int row = rowb + q * nw;
;             if (row < r1) { const float* src = from_out ? p.out + (size_t)row * DM : (row < NP ? p.x_prompt + (size_t)row * DM : p.x_sample + (size_t)(row - NP) * DM);
; #pragma unroll
;                 for (int i = 0; i < 4; ++i) v[q][i] = *(const f32x4*)(src + (i >> 1) * 512 + lane * 8 + (i & 1) * 4); }
;             else {
; #pragma unroll
;                 for (int i = 0; i < 4; ++i) v[q][i] = (f32x4){0.f, 0.f, 0.f, 0.f}; } }
;         __builtin_amdgcn_sched_barrier(0);
;         float rs[4];
; #pragma unroll
;         for (int q = 0; q < 4; ++q) { float ss = 0.f;
; #pragma unroll
;             for (int i = 0; i < 4; ++i) ss += v[q][i][0] * v[q][i][0] + v[q][i][1] * v[q][i][1] + v[q][i][2] * v[q][i][2] + v[q][i][3] * v[q][i][3];
; #pragma unroll
;             for (int o = 1; o < 64; o <<= 1) ss += __shfl_xor(ss, o);
;             rs[q] = rsqrtf(ss * (1.f / DM) + EPS); }
; #pragma unroll
;         for (int q = 0; q < 4; ++q) { const int row = rowb + q * nw;
;             if (row < r1) { const float* mb = mod + (size_t)batch_of(row) * NMOD;
; #pragma unroll
;                 for (int h = 0; h < 2; ++h) { const int c = h * 512 + lane * 8;
;                     const f32x4 y0 = v[q][2 * h] * rs[q] * gv[2 * h], y1 = v[q][2 * h + 1] * rs[q] * gv[2 * h + 1];
.LBB0_142:
	s_or_b64 exec, exec, s[64:65]
	s_waitcnt vmcnt(2)
	v_mov_b32_e32 v106, v61
	v_mov_b32_e32 v107, v57
	v_mov_b32_e32 v104, v60
	v_mov_b32_e32 v105, v56
	v_pk_mul_f32 v[106:107], v[106:107], v[106:107]
	s_waitcnt vmcnt(0)
	v_mov_b32_e32 v108, v53
	v_pk_fma_f32 v[104:105], v[104:105], v[104:105], v[106:107]
	v_mov_b32_e32 v106, v62
	v_mov_b32_e32 v107, v58
	v_pk_fma_f32 v[104:105], v[106:107], v[106:107], v[104:105]
	v_mov_b32_e32 v106, v63
	v_mov_b32_e32 v107, v59
	v_mov_b32_e32 v109, v49
	v_pk_fma_f32 v[104:105], v[106:107], v[106:107], v[104:105]
	v_mov_b32_e32 v106, v52
	v_mov_b32_e32 v107, v48
	v_pk_mul_f32 v[108:109], v[108:109], v[108:109]
	v_ashrrev_i32_e32 v79, 11, v67
	v_pk_fma_f32 v[106:107], v[106:107], v[106:107], v[108:109]
	v_mov_b32_e32 v108, v54
	v_mov_b32_e32 v109, v50
	v_pk_fma_f32 v[106:107], v[108:109], v[108:109], v[106:107]
	v_mov_b32_e32 v108, v55
	v_mov_b32_e32 v109, v51
	v_pk_fma_f32 v[122:123], v[108:109], v[108:109], v[106:107]
	v_add_u32_e32 v106, 0xffffc008, v67
	v_cndmask_b32_e64 v79, v106, v79, s[6:7]
	v_mov_b64_e32 v[106:107], s[16:17]
	v_mad_i64_i32 v[114:115], s[6:7], v79, s13, v[106:107]
	v_lshl_add_u64 v[126:127], v[114:115], 0, s[10:11]
	v_lshl_add_u64 v[110:111], v[126:127], 0, v[80:81]
	global_load_dwordx4 v[106:109], v[110:111], off offset:16
	s_nop 0
	global_load_dwordx4 v[110:113], v[110:111], off
	v_lshl_add_u64 v[128:129], v[114:115], 0, v[80:81]
	global_load_dwordx4 v[114:117], v[128:129], off offset:16
	global_load_dwordx4 v[118:121], v[128:129], off
	v_pk_mul_f32 v[124:125], v[92:93], v[92:93]
	v_pk_mul_f32 v[130:131], v[86:87], v[86:87]
	v_pk_fma_f32 v[124:125], v[24:25], v[24:25], v[124:125]
	v_pk_fma_f32 v[130:131], v[20:21], v[20:21], v[130:131]
	v_pk_fma_f32 v[124:125], v[26:27], v[26:27], v[124:125]
	v_pk_fma_f32 v[130:131], v[22:23], v[22:23], v[130:131]
	v_pk_fma_f32 v[124:125], v[88:89], v[88:89], v[124:125]
	v_pk_fma_f32 v[130:131], v[84:85], v[84:85], v[130:131]
	v_mov_b32_e32 v132, v104
	v_mov_b32_e32 v133, v124
	v_mov_b32_e32 v124, v105
	v_pk_add_f32 v[104:105], v[132:133], v[124:125]
	v_mov_b32_e32 v124, v122
	v_mov_b32_e32 v125, v130
	v_pk_add_f32 v[104:105], v[104:105], v[124:125]
	v_mov_b32_e32 v130, v123
	v_pk_add_f32 v[104:105], v[104:105], v[130:131]
	ds_bpermute_b32 v122, v225, v104
	ds_bpermute_b32 v123, v225, v105
	s_waitcnt lgkmcnt(0)
	v_pk_add_f32 v[104:105], v[104:105], v[122:123]
	ds_bpermute_b32 v122, v226, v104
	ds_bpermute_b32 v123, v226, v105
	s_waitcnt lgkmcnt(0)
	v_pk_add_f32 v[104:105], v[104:105], v[122:123]
	ds_bpermute_b32 v122, v227, v104
	ds_bpermute_b32 v123, v227, v105
	s_waitcnt lgkmcnt(0)
	v_pk_add_f32 v[104:105], v[104:105], v[122:123]
	ds_bpermute_b32 v122, v228, v104
	ds_bpermute_b32 v123, v228, v105
	s_waitcnt lgkmcnt(0)
	v_pk_add_f32 v[104:105], v[104:105], v[122:123]
	ds_bpermute_b32 v122, v229, v104
	ds_bpermute_b32 v123, v229, v105
	s_waitcnt lgkmcnt(0)
	v_pk_add_f32 v[104:105], v[104:105], v[122:123]
	ds_bpermute_b32 v122, v230, v104
	ds_bpermute_b32 v123, v230, v105
	s_waitcnt lgkmcnt(0)
	v_pk_add_f32 v[104:105], v[104:105], v[122:123]
	s_nop 0
	v_pk_fma_f32 v[104:105], v[104:105], s[14:15], v[82:83] op_sel_hi:[1,0,0]
	v_lshl_add_u64 v[122:123], v[76:77], 0, v[70:71]
	v_mul_f32_e32 v79, 0x4b800000, v104
	v_cmp_gt_f32_e64 s[6:7], s15, v104
	s_waitcnt vmcnt(3)
	v_pk_add_f32 v[108:109], v[108:109], 1.0 op_sel_hi:[1,0]
	v_cndmask_b32_e64 v79, v104, v79, s[6:7]
	v_rsq_f32_e32 v79, v79
	s_waitcnt vmcnt(2)
	v_pk_add_f32 v[110:111], v[110:111], 1.0 op_sel_hi:[1,0]
	v_pk_add_f32 v[112:113], v[112:113], 1.0 op_sel_hi:[1,0]
	v_pk_add_f32 v[106:107], v[106:107], 1.0 op_sel_hi:[1,0]
	v_mul_f32_e32 v104, 0x45800000, v79
	v_cndmask_b32_e64 v104, v79, v104, s[6:7]
	v_pk_mul_f32 v[60:61], v[60:61], v[104:105] op_sel_hi:[1,0]
	v_pk_mul_f32 v[62:63], v[62:63], v[104:105] op_sel_hi:[1,0]
	v_pk_mul_f32 v[60:61], v[4:5], v[60:61]
	v_pk_mul_f32 v[58:59], v[58:59], v[104:105] op_sel_hi:[1,0]
	v_pk_mul_f32 v[56:57], v[56:57], v[104:105] op_sel_hi:[1,0]
	v_pk_mul_f32 v[62:63], v[6:7], v[62:63]
	v_pk_mul_f32 v[56:57], v[0:1], v[56:57]
	v_pk_mul_f32 v[58:59], v[2:3], v[58:59]
	s_waitcnt vmcnt(0)
; __device__ __forceinline__ void st_bf16x8(bf16_t* p, const f32x4 a, const f32x4 b) { uint4 o; o.x = cvt_pk_bf16(a[0], a[1]); o.y = cvt_pk_bf16(a[2], a[3]); o.z = cvt_pk_bf16(b[0], b[1]); o.w = cvt_pk_bf16(b[2], b[3]); *(uint4*)p = o; }
;     ...
;         for (int q = 0; q < 4; ++q) { const int row = rowb + q * nw;
;             if (row < r1) { const float* mb = mod + (size_t)batch_of(row) * NMOD;
; #pragma unroll
;                 for (int h = 0; h < 2; ++h) { const int c = h * 512 + lane * 8;
;                     const f32x4 y0 = v[q][2 * h] * rs[q] * gv[2 * h], y1 = v[q][2 * h + 1] * rs[q] * gv[2 * h + 1];
;                     if (FINAL) { *(f32x4*)(p.out + (size_t)row * DM + c) = y0; *(f32x4*)(p.out + (size_t)row * DM + c + 4) = y1; }
;                     else { if (WT) st_wt_bf16x8(H + (size_t)row * DM + c, y0 * (*(const f32x4*)(mb + sc_off + c) + 1.f) + *(const f32x4*)(mb + sh_off + c),
;                                                              y1 * (*(const f32x4*)(mb + sc_off + c + 4) + 1.f) + *(const f32x4*)(mb + sh_off + c + 4)); else st_bf16x8(H + (size_t)row * DM + c, y0 * (*(const f32x4*)(mb + sc_off + c) + 1.f) + *(const f32x4*)(mb + sh_off + c),
;                                                              y1 * (*(const f32x4*)(mb + sc_off + c + 4) + 1.f) + *(const f32x4*)(mb + sh_off + c + 4)); } } } }
	v_pk_fma_f32 v[60:61], v[60:61], v[110:111], v[118:119]
	v_add_co_u32_e64 v118, s[6:7], s66, v122
	v_pk_fma_f32 v[62:63], v[62:63], v[112:113], v[120:121]
	v_pk_fma_f32 v[108:109], v[58:59], v[108:109], v[116:117]
	v_pk_fma_f32 v[58:59], v[56:57], v[106:107], v[114:115]
	v_cvt_pk_bf16_f32 v56, v60, v61
	v_cvt_pk_bf16_f32 v57, v62, v63
	v_addc_co_u32_e64 v119, s[6:7], 0, v123, s[6:7]
	v_mov_b32_e32 v79, v81
	v_cvt_pk_bf16_f32 v58, v58, v59
	v_cvt_pk_bf16_f32 v59, v108, v109
	global_store_dwordx4 v[118:119], v[56:59], off sc1
	v_pk_mul_f32 v[54:55], v[54:55], v[104:105] op_sel_hi:[1,0]
	v_pk_mul_f32 v[52:53], v[52:53], v[104:105] op_sel_hi:[1,0]
	v_lshl_add_u64 v[56:57], v[126:127], 0, v[78:79]
	global_load_dwordx4 v[60:63], v[56:57], off
	global_load_dwordx4 v[106:109], v[128:129], off offset:2048
	global_load_dwordx4 v[110:113], v[56:57], off offset:16
	global_load_dwordx4 v[114:117], v[128:129], off offset:2064
	v_mul_f32_e32 v56, v45, v45
	v_mul_f32_e32 v57, v41, v41
	v_fmac_f32_e32 v56, v44, v44
	v_fmac_f32_e32 v57, v40, v40
	v_fmac_f32_e32 v56, v46, v46
	v_fmac_f32_e32 v57, v42, v42
	v_fmac_f32_e32 v56, v47, v47
	v_fmac_f32_e32 v57, v43, v43
	v_add_f32_e32 v56, v57, v56
	v_mul_f32_e32 v57, v37, v37
	v_fmac_f32_e32 v57, v36, v36
	v_fmac_f32_e32 v57, v38, v38
	v_fmac_f32_e32 v57, v39, v39
	v_add_f32_e32 v56, v57, v56
	v_mul_f32_e32 v57, v33, v33
	v_fmac_f32_e32 v57, v32, v32
	v_fmac_f32_e32 v57, v34, v34
	v_fmac_f32_e32 v57, v35, v35
	v_add_f32_e32 v120, v57, v56
	v_pk_mul_f32 v[56:57], v[102:103], v[102:103]
	v_pk_mul_f32 v[58:59], v[94:95], v[94:95]
	v_pk_fma_f32 v[56:57], v[28:29], v[28:29], v[56:57]
	v_pk_fma_f32 v[58:59], v[16:17], v[16:17], v[58:59]
	v_pk_fma_f32 v[56:57], v[30:31], v[30:31], v[56:57]
	v_pk_fma_f32 v[58:59], v[18:19], v[18:19], v[58:59]
	v_pk_fma_f32 v[56:57], v[100:101], v[100:101], v[56:57]
	v_pk_fma_f32 v[58:59], v[96:97], v[96:97], v[58:59]
	v_add_f32_e32 v56, v56, v57
	v_add_f32_e32 v56, v59, v56
	v_add_f32_e32 v56, v58, v56
	ds_bpermute_b32 v121, v225, v120
	ds_bpermute_b32 v57, v225, v56
	v_pk_mul_f32 v[52:53], v[12:13], v[52:53]
	v_pk_mul_f32 v[54:55], v[14:15], v[54:55]
	v_pk_mul_f32 v[50:51], v[50:51], v[104:105] op_sel_hi:[1,0]
	s_waitcnt lgkmcnt(1)
	v_add_f32_e32 v58, v120, v121
	s_waitcnt lgkmcnt(0)
	v_add_f32_e32 v56, v56, v57
	ds_bpermute_b32 v59, v226, v58
	ds_bpermute_b32 v57, v226, v56
	v_pk_mul_f32 v[48:49], v[48:49], v[104:105] op_sel_hi:[1,0]
	v_pk_mul_f32 v[50:51], v[10:11], v[50:51]
	v_pk_mul_f32 v[48:49], v[8:9], v[48:49]
	s_waitcnt lgkmcnt(1)
	v_add_f32_e32 v58, v58, v59
	s_waitcnt lgkmcnt(0)
	v_add_f32_e32 v56, v56, v57
	ds_bpermute_b32 v59, v227, v58
	ds_bpermute_b32 v57, v227, v56
	v_cmp_gt_f32_e64 s[6:7], s15, v105
	s_waitcnt lgkmcnt(1)
	v_add_f32_e32 v58, v58, v59
	s_waitcnt lgkmcnt(0)
	v_add_f32_e32 v56, v56, v57
	ds_bpermute_b32 v59, v228, v58
	ds_bpermute_b32 v57, v228, v56
	s_waitcnt lgkmcnt(1)
	v_add_f32_e32 v58, v58, v59
	s_waitcnt lgkmcnt(0)
	v_add_f32_e32 v56, v56, v57
	ds_bpermute_b32 v59, v229, v58
	ds_bpermute_b32 v57, v229, v56
	s_waitcnt lgkmcnt(1)
	v_add_f32_e32 v58, v58, v59
	s_waitcnt lgkmcnt(0)
	v_add_f32_e32 v56, v56, v57
	ds_bpermute_b32 v59, v230, v58
	ds_bpermute_b32 v57, v230, v56
	s_waitcnt vmcnt(3)
	v_pk_add_f32 v[62:63], v[62:63], 1.0 op_sel_hi:[1,0]
	v_pk_add_f32 v[60:61], v[60:61], 1.0 op_sel_hi:[1,0]
	s_waitcnt vmcnt(2)
	v_pk_fma_f32 v[54:55], v[54:55], v[62:63], v[108:109]
	v_pk_fma_f32 v[52:53], v[52:53], v[60:61], v[106:107]
	s_waitcnt vmcnt(1)
	v_pk_add_f32 v[60:61], v[112:113], 1.0 op_sel_hi:[1,0]
	v_pk_add_f32 v[62:63], v[110:111], 1.0 op_sel_hi:[1,0]
	s_waitcnt vmcnt(0)
	v_pk_fma_f32 v[60:61], v[50:51], v[60:61], v[116:117]
	v_pk_fma_f32 v[50:51], v[48:49], v[62:63], v[114:115]
	v_cvt_pk_bf16_f32 v48, v52, v53
	v_cvt_pk_bf16_f32 v49, v54, v55
	s_nop 0
	v_cvt_pk_bf16_f32 v50, v50, v51
	v_cvt_pk_bf16_f32 v51, v60, v61
	global_store_dwordx4 v[118:119], v[48:51], off offset:1024 sc1
	s_and_saveexec_b64 s[64:65], s[4:5]
	s_cbranch_execnz .LBB0_145
	s_or_b64 exec, exec, s[64:65]
	s_and_saveexec_b64 s[4:5], s[0:1]
	s_cbranch_execnz .LBB0_146

; __device__ __forceinline__ void st_bf16x8(bf16_t* p, const f32x4 a, const f32x4 b) { uint4 o; o.x = cvt_pk_bf16(a[0], a[1]); o.y = cvt_pk_bf16(a[2], a[3]); o.z = cvt_pk_bf16(b[0], b[1]); o.w = cvt_pk_bf16(b[2], b[3]); *(uint4*)p = o; }
;     ...
;             rs[q] = rsqrtf(ss * (1.f / DM) + EPS); }
; #pragma unroll
;         for (int q = 0; q < 4; ++q) { const int row = rowb + q * nw;
;             if (row < r1) { const float* mb = mod + (size_t)batch_of(row) * NMOD;
; #pragma unroll
;                 for (int h = 0; h < 2; ++h) { const int c = h * 512 + lane * 8;
;                     const f32x4 y0 = v[q][2 * h] * rs[q] * gv[2 * h], y1 = v[q][2 * h + 1] * rs[q] * gv[2 * h + 1];
;                     if (FINAL) { *(f32x4*)(p.out + (size_t)row * DM + c) = y0; *(f32x4*)(p.out + (size_t)row * DM + c + 4) = y1; }
;                     else { if (WT) st_wt_bf16x8(H + (size_t)row * DM + c, y0 * (*(const f32x4*)(mb + sc_off + c) + 1.f) + *(const f32x4*)(mb + sh_off + c),
;                                                              y1 * (*(const f32x4*)(mb + sc_off + c + 4) + 1.f) + *(const f32x4*)(mb + sh_off + c + 4)); else st_bf16x8(H + (size_t)row * DM + c, y0 * (*(const f32x4*)(mb + sc_off + c) + 1.f) + *(const f32x4*)(mb + sh_off + c),
;                                                              y1 * (*(const f32x4*)(mb + sc_off + c + 4) + 1.f) + *(const f32x4*)(mb + sh_off + c + 4)); } } } }
.LBB0_145:
	v_ashrrev_i32_e32 v48, 11, v83
	v_add_u32_e32 v49, 0xffffc008, v83
	v_cmp_gt_i32_e64 s[4:5], s12, v83
	s_waitcnt lgkmcnt(1)
	v_add_f32_e32 v83, v58, v59
	v_fmamk_f32 v83, v83, 0x3a800000, v82
	v_cndmask_b32_e64 v50, v49, v48, s[4:5]
	v_mov_b64_e32 v[48:49], s[16:17]
	v_mad_i64_i32 v[60:61], s[4:5], v50, s13, v[48:49]
	v_lshl_add_u64 v[110:111], v[60:61], 0, s[10:11]
	v_lshl_add_u64 v[52:53], v[110:111], 0, v[80:81]
	global_load_dwordx4 v[48:51], v[52:53], off
	s_nop 0
	global_load_dwordx4 v[52:55], v[52:53], off offset:16
	v_lshl_add_u64 v[112:113], v[60:61], 0, v[80:81]
	global_load_dwordx4 v[60:63], v[112:113], off
	global_load_dwordx4 v[106:109], v[112:113], off offset:16
	v_mul_f32_e32 v104, 0x4b800000, v83
	v_cmp_gt_f32_e64 s[4:5], s15, v83
	v_lshl_add_u64 v[110:111], v[110:111], 0, v[78:79]
	v_lshl_add_u64 v[58:59], v[74:75], 0, v[70:71]
	v_cndmask_b32_e64 v83, v83, v104, s[4:5]
	v_rsq_f32_e32 v83, v83
	v_add_co_u32_e64 v58, s[8:9], s66, v58
	v_mul_f32_e32 v79, 0x45800000, v83
	v_cndmask_b32_e64 v104, v83, v79, s[4:5]
	v_pk_mul_f32 v[44:45], v[44:45], v[104:105] op_sel_hi:[1,0]
	v_pk_mul_f32 v[42:43], v[42:43], v[104:105] op_sel_hi:[1,0]
	v_pk_mul_f32 v[40:41], v[40:41], v[104:105] op_sel_hi:[1,0]
	v_pk_mul_f32 v[46:47], v[46:47], v[104:105] op_sel_hi:[1,0]
	v_pk_mul_f32 v[44:45], v[4:5], v[44:45]
	v_pk_mul_f32 v[40:41], v[0:1], v[40:41]
	v_pk_mul_f32 v[42:43], v[2:3], v[42:43]
	v_addc_co_u32_e64 v59, s[8:9], 0, v59, s[8:9]
	v_pk_mul_f32 v[46:47], v[6:7], v[46:47]
	v_pk_mul_f32 v[36:37], v[36:37], v[104:105] op_sel_hi:[1,0]
	v_pk_mul_f32 v[34:35], v[34:35], v[104:105] op_sel_hi:[1,0]
	v_pk_mul_f32 v[32:33], v[32:33], v[104:105] op_sel_hi:[1,0]
	v_pk_mul_f32 v[38:39], v[38:39], v[104:105] op_sel_hi:[1,0]
	v_pk_mul_f32 v[36:37], v[12:13], v[36:37]
	v_pk_mul_f32 v[32:33], v[8:9], v[32:33]
	v_pk_mul_f32 v[34:35], v[10:11], v[34:35]
	v_pk_mul_f32 v[38:39], v[14:15], v[38:39]
	s_waitcnt vmcnt(3)
	v_pk_add_f32 v[48:49], v[48:49], 1.0 op_sel_hi:[1,0]
	s_waitcnt vmcnt(2)
	v_pk_add_f32 v[54:55], v[54:55], 1.0 op_sel_hi:[1,0]
	v_pk_add_f32 v[52:53], v[52:53], 1.0 op_sel_hi:[1,0]
	v_pk_add_f32 v[50:51], v[50:51], 1.0 op_sel_hi:[1,0]
	s_waitcnt vmcnt(1)
	v_pk_fma_f32 v[44:45], v[44:45], v[48:49], v[60:61]
	s_waitcnt vmcnt(0)
	v_pk_fma_f32 v[48:49], v[42:43], v[54:55], v[108:109]
	v_pk_fma_f32 v[42:43], v[40:41], v[52:53], v[106:107]
	v_pk_fma_f32 v[46:47], v[46:47], v[50:51], v[62:63]
	v_cvt_pk_bf16_f32 v40, v44, v45
	v_cvt_pk_bf16_f32 v42, v42, v43
	v_cvt_pk_bf16_f32 v43, v48, v49
	s_nop 0
	v_cvt_pk_bf16_f32 v41, v46, v47
	global_store_dwordx4 v[58:59], v[40:43], off sc1
	global_load_dwordx4 v[40:43], v[110:111], off
	s_nop 0
	global_load_dwordx4 v[44:47], v[110:111], off offset:16
	global_load_dwordx4 v[48:51], v[112:113], off offset:2048
	global_load_dwordx4 v[52:55], v[112:113], off offset:2064
	s_waitcnt vmcnt(3)
	v_pk_add_f32 v[40:41], v[40:41], 1.0 op_sel_hi:[1,0]
	s_waitcnt vmcnt(2)
	v_pk_add_f32 v[46:47], v[46:47], 1.0 op_sel_hi:[1,0]
	v_pk_add_f32 v[44:45], v[44:45], 1.0 op_sel_hi:[1,0]
	v_pk_add_f32 v[42:43], v[42:43], 1.0 op_sel_hi:[1,0]
	s_waitcnt vmcnt(1)
	v_pk_fma_f32 v[36:37], v[36:37], v[40:41], v[48:49]
	s_waitcnt vmcnt(0)
	v_pk_fma_f32 v[40:41], v[34:35], v[46:47], v[54:55]
	v_pk_fma_f32 v[34:35], v[32:33], v[44:45], v[52:53]
	v_pk_fma_f32 v[38:39], v[38:39], v[42:43], v[50:51]
	v_cvt_pk_bf16_f32 v32, v36, v37
	v_cvt_pk_bf16_f32 v34, v34, v35
	v_cvt_pk_bf16_f32 v35, v40, v41
	s_nop 0
	v_cvt_pk_bf16_f32 v33, v38, v39
	global_store_dwordx4 v[58:59], v[32:35], off offset:1024 sc1
	s_or_b64 exec, exec, s[64:65]
	s_and_saveexec_b64 s[4:5], s[0:1]
	s_cbranch_execz .LBB0_144
.LBB0_146:
	v_ashrrev_i32_e32 v32, 11, v98
	v_add_u32_e32 v33, 0xffffc008, v98
	v_cmp_gt_i32_e64 s[0:1], s12, v98
	s_waitcnt lgkmcnt(0)
	v_add_f32_e32 v58, v56, v57
	v_fmamk_f32 v58, v58, 0x3a800000, v82
	v_cndmask_b32_e64 v34, v33, v32, s[0:1]
	v_mov_b64_e32 v[32:33], s[16:17]
	v_mad_i64_i32 v[40:41], s[0:1], v34, s13, v[32:33]
	v_lshl_add_u64 v[48:49], v[40:41], 0, s[10:11]
	v_lshl_add_u64 v[36:37], v[48:49], 0, v[80:81]
	global_load_dwordx4 v[32:35], v[36:37], off
	s_nop 0
	global_load_dwordx4 v[36:39], v[36:37], off offset:16
	v_lshl_add_u64 v[50:51], v[40:41], 0, v[80:81]
	global_load_dwordx4 v[40:43], v[50:51], off
	global_load_dwordx4 v[44:47], v[50:51], off offset:16
	v_mul_f32_e32 v59, 0x4b800000, v58
	v_cmp_gt_f32_e64 s[0:1], s15, v58
	v_mov_b32_e32 v52, v29
	v_mov_b32_e32 v29, v102
	v_cndmask_b32_e64 v58, v58, v59, s[0:1]
	v_rsq_f32_e32 v58, v58
	v_mov_b32_e32 v56, v31
	v_mov_b32_e32 v31, v100
	v_mov_b32_e32 v53, v103
	v_mul_f32_e32 v59, 0x45800000, v58
	v_cndmask_b32_e64 v58, v58, v59, s[0:1]
	v_mov_b32_e32 v57, v101
	v_pk_mul_f32 v[30:31], v[30:31], v[58:59] op_sel_hi:[1,0]
	v_pk_mul_f32 v[28:29], v[28:29], v[58:59] op_sel_hi:[1,0]
	v_lshlrev_b64 v[54:55], 11, v[98:99]
	v_pk_mul_f32 v[56:57], v[56:57], v[58:59] op_sel_hi:[1,0]
	v_pk_mul_f32 v[52:53], v[52:53], v[58:59] op_sel_hi:[1,0]
	v_pk_mul_f32 v[28:29], v[0:1], v[28:29]
	v_pk_mul_f32 v[30:31], v[2:3], v[30:31]
	v_mov_b32_e32 v79, v81
	v_lshl_add_u64 v[54:55], v[68:69], 0, v[54:55]
	v_pk_mul_f32 v[52:53], v[4:5], v[52:53]
	v_pk_mul_f32 v[56:57], v[6:7], v[56:57]
	v_lshl_add_u64 v[48:49], v[48:49], 0, v[78:79]
	s_waitcnt vmcnt(3)
	v_pk_add_f32 v[34:35], v[34:35], 1.0 op_sel_hi:[1,0]
	s_waitcnt vmcnt(2)
	v_pk_add_f32 v[38:39], v[38:39], 1.0 op_sel_hi:[1,0]
	v_pk_add_f32 v[36:37], v[36:37], 1.0 op_sel_hi:[1,0]
	v_pk_add_f32 v[32:33], v[32:33], 1.0 op_sel_hi:[1,0]
	s_waitcnt vmcnt(0)
; __device__ __forceinline__ void st_bf16x8(bf16_t* p, const f32x4 a, const f32x4 b) { uint4 o; o.x = cvt_pk_bf16(a[0], a[1]); o.y = cvt_pk_bf16(a[2], a[3]); o.z = cvt_pk_bf16(b[0], b[1]); o.w = cvt_pk_bf16(b[2], b[3]); *(uint4*)p = o; }
;     ...
;         for (int q = 0; q < 4; ++q) { const int row = rowb + q * nw;
;             if (row < r1) { const float* mb = mod + (size_t)batch_of(row) * NMOD;
; #pragma unroll
;                 for (int h = 0; h < 2; ++h) { const int c = h * 512 + lane * 8;
;                     const f32x4 y0 = v[q][2 * h] * rs[q] * gv[2 * h], y1 = v[q][2 * h + 1] * rs[q] * gv[2 * h + 1];
;                     if (FINAL) { *(f32x4*)(p.out + (size_t)row * DM + c) = y0; *(f32x4*)(p.out + (size_t)row * DM + c + 4) = y1; }
;                     else { if (WT) st_wt_bf16x8(H + (size_t)row * DM + c, y0 * (*(const f32x4*)(mb + sc_off + c) + 1.f) + *(const f32x4*)(mb + sh_off + c),
;                                                              y1 * (*(const f32x4*)(mb + sc_off + c + 4) + 1.f) + *(const f32x4*)(mb + sh_off + c + 4)); else st_bf16x8(H + (size_t)row * DM + c, y0 * (*(const f32x4*)(mb + sc_off + c) + 1.f) + *(const f32x4*)(mb + sh_off + c),
;                                                              y1 * (*(const f32x4*)(mb + sc_off + c + 4) + 1.f) + *(const f32x4*)(mb + sh_off + c + 4)); } } } }
	v_pk_fma_f32 v[38:39], v[30:31], v[38:39], v[46:47]
	v_pk_fma_f32 v[30:31], v[28:29], v[36:37], v[44:45]
	v_pk_fma_f32 v[34:35], v[56:57], v[34:35], v[42:43]
	v_pk_fma_f32 v[32:33], v[52:53], v[32:33], v[40:41]
	v_cvt_pk_bf16_f32 v29, v34, v35
	v_cvt_pk_bf16_f32 v30, v30, v31
	v_cvt_pk_bf16_f32 v31, v38, v39
	v_mov_b32_e32 v44, v17
	v_cvt_pk_bf16_f32 v28, v32, v33
	global_store_dwordx4 v[54:55], v[28:31], off sc1
	global_load_dwordx4 v[28:31], v[48:49], off
	s_nop 0
	global_load_dwordx4 v[32:35], v[48:49], off offset:16
	global_load_dwordx4 v[36:39], v[50:51], off offset:2048
	global_load_dwordx4 v[40:43], v[50:51], off offset:2064
	v_mov_b32_e32 v17, v94
	v_mov_b32_e32 v46, v19
	v_mov_b32_e32 v19, v96
	v_mov_b32_e32 v45, v95
	v_mov_b32_e32 v47, v97
	v_pk_mul_f32 v[18:19], v[18:19], v[58:59] op_sel_hi:[1,0]
	v_pk_mul_f32 v[16:17], v[16:17], v[58:59] op_sel_hi:[1,0]
	v_pk_mul_f32 v[46:47], v[46:47], v[58:59] op_sel_hi:[1,0]
	v_pk_mul_f32 v[44:45], v[44:45], v[58:59] op_sel_hi:[1,0]
	v_pk_mul_f32 v[16:17], v[8:9], v[16:17]
	v_pk_mul_f32 v[18:19], v[10:11], v[18:19]
	v_pk_mul_f32 v[44:45], v[12:13], v[44:45]
	v_pk_mul_f32 v[46:47], v[14:15], v[46:47]
	s_waitcnt vmcnt(3)
	v_pk_add_f32 v[30:31], v[30:31], 1.0 op_sel_hi:[1,0]
	s_waitcnt vmcnt(2)
	v_pk_add_f32 v[34:35], v[34:35], 1.0 op_sel_hi:[1,0]
	v_pk_add_f32 v[32:33], v[32:33], 1.0 op_sel_hi:[1,0]
	v_pk_add_f32 v[28:29], v[28:29], 1.0 op_sel_hi:[1,0]
	s_waitcnt vmcnt(0)
	v_pk_fma_f32 v[34:35], v[18:19], v[34:35], v[42:43]
	v_pk_fma_f32 v[18:19], v[16:17], v[32:33], v[40:41]
	v_pk_fma_f32 v[30:31], v[46:47], v[30:31], v[38:39]
	v_pk_fma_f32 v[28:29], v[44:45], v[28:29], v[36:37]
	v_cvt_pk_bf16_f32 v17, v30, v31
	v_cvt_pk_bf16_f32 v18, v18, v19
	v_cvt_pk_bf16_f32 v19, v34, v35
	s_nop 0
	v_cvt_pk_bf16_f32 v16, v28, v29
	global_store_dwordx4 v[54:55], v[16:19], off offset:1024 sc1
	s_or_b64 exec, exec, s[4:5]
	s_and_saveexec_b64 s[0:1], vcc
	s_cbranch_execz .LBB0_135
.LBB0_147:
	v_ashrrev_i32_e32 v16, 11, v90
	v_add_u32_e32 v17, 0xffffc008, v90
	v_cmp_gt_i32_e32 vcc, s12, v90
	v_mul_f32_e32 v50, 0x4b800000, v105
	v_mov_b32_e32 v48, v26
	v_cndmask_b32_e32 v18, v17, v16, vcc
	v_mov_b64_e32 v[16:17], s[16:17]
	v_mad_i64_i32 v[32:33], s[4:5], v18, s13, v[16:17]
	v_lshl_add_u64 v[40:41], v[32:33], 0, s[10:11]
	v_lshl_add_u64 v[28:29], v[40:41], 0, v[80:81]
	global_load_dwordx4 v[16:19], v[28:29], off
	s_nop 0
	global_load_dwordx4 v[28:31], v[28:29], off offset:16
	v_lshl_add_u64 v[42:43], v[32:33], 0, v[80:81]
	global_load_dwordx4 v[32:35], v[42:43], off
	global_load_dwordx4 v[36:39], v[42:43], off offset:16
	v_cndmask_b32_e64 v26, v105, v50, s[6:7]
	v_rsq_f32_e32 v50, v26
	v_mov_b32_e32 v79, v81
	v_mov_b32_e32 v49, v88
	v_mov_b32_e32 v88, v27
	v_lshl_add_u64 v[26:27], v[40:41], 0, v[78:79]
	v_mul_f32_e32 v40, 0x45800000, v50
	v_mov_b32_e32 v44, v25
	v_mov_b32_e32 v25, v92
	v_cndmask_b32_e64 v40, v50, v40, s[6:7]
	v_mov_b32_e32 v45, v93
	v_pk_mul_f32 v[48:49], v[48:49], v[40:41] op_sel_hi:[1,0]
	v_pk_mul_f32 v[24:25], v[24:25], v[40:41] op_sel_hi:[1,0]
	v_lshlrev_b64 v[46:47], 11, v[90:91]
	v_pk_mul_f32 v[50:51], v[88:89], v[40:41] op_sel_hi:[1,0]
	v_pk_mul_f32 v[44:45], v[44:45], v[40:41] op_sel_hi:[1,0]
	v_pk_mul_f32 v[24:25], v[4:5], v[24:25]
	v_pk_mul_f32 v[48:49], v[6:7], v[48:49]
	v_lshl_add_u64 v[46:47], v[68:69], 0, v[46:47]
	v_pk_mul_f32 v[44:45], v[0:1], v[44:45]
	v_pk_mul_f32 v[50:51], v[2:3], v[50:51]
	s_waitcnt vmcnt(3)
	v_pk_add_f32 v[18:19], v[18:19], 1.0 op_sel_hi:[1,0]
	v_pk_add_f32 v[16:17], v[16:17], 1.0 op_sel_hi:[1,0]
	s_waitcnt vmcnt(2)
	v_pk_add_f32 v[30:31], v[30:31], 1.0 op_sel_hi:[1,0]
	v_pk_add_f32 v[28:29], v[28:29], 1.0 op_sel_hi:[1,0]
	s_waitcnt vmcnt(1)
	v_pk_fma_f32 v[18:19], v[48:49], v[18:19], v[34:35]
	v_pk_fma_f32 v[16:17], v[24:25], v[16:17], v[32:33]
	s_waitcnt vmcnt(0)
	v_pk_fma_f32 v[24:25], v[50:51], v[30:31], v[38:39]
	v_pk_fma_f32 v[28:29], v[44:45], v[28:29], v[36:37]
	v_cvt_pk_bf16_f32 v16, v16, v17
	v_cvt_pk_bf16_f32 v17, v18, v19
	v_cvt_pk_bf16_f32 v19, v24, v25
	v_mov_b32_e32 v36, v21
	v_cvt_pk_bf16_f32 v18, v28, v29
	global_store_dwordx4 v[46:47], v[16:19], off sc1
	global_load_dwordx4 v[16:19], v[26:27], off
	s_nop 0
	global_load_dwordx4 v[24:27], v[26:27], off offset:16
	s_nop 0
	global_load_dwordx4 v[28:31], v[42:43], off offset:2048
	global_load_dwordx4 v[32:35], v[42:43], off offset:2064
	v_mov_b32_e32 v21, v86
	v_mov_b32_e32 v38, v22
	v_mov_b32_e32 v39, v84
	v_mov_b32_e32 v37, v87
	v_mov_b32_e32 v84, v23
	v_pk_mul_f32 v[22:23], v[38:39], v[40:41] op_sel_hi:[1,0]
	v_pk_mul_f32 v[20:21], v[20:21], v[40:41] op_sel_hi:[1,0]
	v_pk_mul_f32 v[38:39], v[84:85], v[40:41] op_sel_hi:[1,0]
	v_pk_mul_f32 v[36:37], v[36:37], v[40:41] op_sel_hi:[1,0]
	v_pk_mul_f32 v[20:21], v[12:13], v[20:21]
	v_pk_mul_f32 v[22:23], v[14:15], v[22:23]
	v_pk_mul_f32 v[36:37], v[8:9], v[36:37]
	v_pk_mul_f32 v[38:39], v[10:11], v[38:39]
	s_waitcnt vmcnt(3)
	v_pk_add_f32 v[18:19], v[18:19], 1.0 op_sel_hi:[1,0]
	v_pk_add_f32 v[16:17], v[16:17], 1.0 op_sel_hi:[1,0]
	s_waitcnt vmcnt(2)
	v_pk_add_f32 v[26:27], v[26:27], 1.0 op_sel_hi:[1,0]
	v_pk_add_f32 v[24:25], v[24:25], 1.0 op_sel_hi:[1,0]
	s_waitcnt vmcnt(1)
	v_pk_fma_f32 v[18:19], v[22:23], v[18:19], v[30:31]
	v_pk_fma_f32 v[16:17], v[20:21], v[16:17], v[28:29]
	s_waitcnt vmcnt(0)
	v_pk_fma_f32 v[20:21], v[38:39], v[26:27], v[34:35]
	v_pk_fma_f32 v[22:23], v[36:37], v[24:25], v[32:33]
	v_cvt_pk_bf16_f32 v16, v16, v17
	v_cvt_pk_bf16_f32 v17, v18, v19
	v_cvt_pk_bf16_f32 v19, v20, v21
	s_nop 0
	v_cvt_pk_bf16_f32 v18, v22, v23
	global_store_dwordx4 v[46:47], v[16:19], off offset:1024 sc1
	s_branch .LBB0_135
